# ROW1 router: both MFMA operands staged through LDS by DMA in 8 K-chunks (coalesced swizzled 128B pieces, ds_read_b128 fragments) instead of 16B-per-lane global loads from 64 lines/instr; same MFMA ord
# speedup vs baseline: 1.0304x; 1.0304x over previous
; __device__ __forceinline__ void phase_row1(const Frame& F, int l) {
;     ...
;         {
;             const int fr = lane & 15, fq = lane >> 4, tile = w >> 1, nt = w & 1;
;             const float* wp = (const float*)(F.ws + WS_RWT) + ((size_t)l * NE + 16 * nt + fr) * D + 256 * fq;
;             const float* hp = H32 + (size_t)(chunk * 64 + 16 * tile + fr) * D + 256 * fq;
;             f32x4 c = {0.f, 0.f, 0.f, 0.f};
; #pragma unroll 16
;             for (int s4 = 0; s4 < 256; s4 += 4) { const f32x4 a = *(const f32x4*)(wp + s4), bq = *(const f32x4*)(hp + s4);
;                 c = __builtin_amdgcn_mfma_f32_16x16x4f32(a.x, bq.x, c, 0, 0, 0); c = __builtin_amdgcn_mfma_f32_16x16x4f32(a.y, bq.y, c, 0, 0, 0);
;                 c = __builtin_amdgcn_mfma_f32_16x16x4f32(a.z, bq.z, c, 0, 0, 0); c = __builtin_amdgcn_mfma_f32_16x16x4f32(a.w, bq.w, c, 0, 0, 0); }
.LBB0_2151:
	v_readfirstlane_b32 s4, v0
	v_readfirstlane_b32 s5, v134
	v_and_b32_e32 v22, 63, v0
	v_lshrrev_b32_e32 v23, 5, v22
	s_lshr_b32 s6, s4, 7
	s_lshl_b32 s6, s6, 4
	s_sub_i32 s5, s5, s6
	s_lshr_b32 s6, s4, 3
	s_add_i32 s5, s5, s6
	v_add_u32_e32 v24, s5, v23
	v_mov_b32_e32 v25, 0
	v_lshlrev_b64 v[24:25], 12, v[24:25]
	v_lshl_add_u64 v[24:25], s[78:79], 0, v[24:25]
	v_lshlrev_b32_e32 v26, 7, v22
	v_and_b32_e32 v26, 0xc00, v26
	v_and_b32_e32 v27, 7, v22
	v_xor_b32_e32 v27, v27, v23
	v_lshlrev_b32_e32 v27, 4, v27
	v_mov_b32_e32 v29, 0
	s_mov_b32 s7, 0
	s_mov_b32 s6, 0x11000000
	v_xor_b32_e32 v28, 0, v27
	v_or_b32_e32 v28, v28, v26
	v_lshl_add_u64 v[30:31], v[24:25], 0, s[6:7]
	v_lshl_add_u64 v[30:31], v[30:31], 0, v[28:29]
	s_mov_b32 s6, 0x11002000
	v_xor_b32_e32 v28, 32, v27
	v_or_b32_e32 v28, v28, v26
	v_lshl_add_u64 v[32:33], v[24:25], 0, s[6:7]
	v_lshl_add_u64 v[32:33], v[32:33], 0, v[28:29]
	s_mov_b32 s6, 0x11004000
	v_xor_b32_e32 v28, 64, v27
	v_or_b32_e32 v28, v28, v26
	v_lshl_add_u64 v[34:35], v[24:25], 0, s[6:7]
	v_lshl_add_u64 v[34:35], v[34:35], 0, v[28:29]
	s_mov_b32 s6, 0x11006000
	v_xor_b32_e32 v28, 0x60, v27
	v_or_b32_e32 v28, v28, v26
	v_lshl_add_u64 v[36:37], v[24:25], 0, s[6:7]
	v_lshl_add_u64 v[36:37], v[36:37], 0, v[28:29]
	s_lshl_b32 s5, s96, 5
	s_lshr_b32 s6, s4, 4
	s_add_i32 s5, s5, s6
	v_add_u32_e32 v24, s5, v23
	v_mov_b32_e32 v25, 0
	v_lshlrev_b64 v[24:25], 12, v[24:25]
	v_lshl_add_u64 v[24:25], s[78:79], 0, v[24:25]
	s_and_b32 s5, s4, 64
	s_add_i32 vcc_lo, s5, 0
	v_xor_b32_e32 v28, vcc_lo, v27
	v_or_b32_e32 v28, v28, v26
	s_mov_b32 s6, 0x70400000
	v_lshl_add_u64 v[38:39], v[24:25], 0, s[6:7]
	v_lshl_add_u64 v[38:39], v[38:39], 0, v[28:29]
	s_add_i32 vcc_lo, s5, 32
	v_xor_b32_e32 v28, vcc_lo, v27
	v_or_b32_e32 v28, v28, v26
	s_mov_b32 s6, 0x70402000
	v_lshl_add_u64 v[40:41], v[24:25], 0, s[6:7]
	v_lshl_add_u64 v[40:41], v[40:41], 0, v[28:29]
	v_and_b32_e32 v42, 15, v0
	v_lshlrev_b32_e32 v43, 9, v42
	v_and_b32_e32 v44, 7, v42
	v_lshl_or_b32 v43, v44, 4, v43
	v_lshrrev_b32_e32 v44, 4, v22
	v_lshl_or_b32 v43, v44, 7, v43
	s_lshr_b32 s5, s4, 7
	s_lshl_b32 s5, s5, 13
	s_add_i32 s5, s5, 0x8000
	v_add_u32_e32 v42, s5, v43
	s_and_b32 s5, s4, 64
	s_lshl_b32 s5, s5, 7
	s_add_i32 s5, s5, 0x10000
	v_add_u32_e32 v43, s5, v43
	s_lshl_b32 s5, s4, 6
	s_lshl_b32 s6, s4, 5
	s_mov_b64 vcc, 0x80
	s_add_i32 m0, s5, 0x8000
	s_nop 0
	global_load_lds_dwordx4 v[30:31], off
	s_add_i32 m0, s5, 0x8400
	s_nop 0
	global_load_lds_dwordx4 v[32:33], off
	s_add_i32 m0, s5, 0x8800
	s_nop 0
	global_load_lds_dwordx4 v[34:35], off
	s_add_i32 m0, s5, 0x8c00
	s_nop 0
	global_load_lds_dwordx4 v[36:37], off
	s_add_i32 m0, s6, 0x10000
	s_nop 0
	global_load_lds_dwordx4 v[38:39], off
	s_add_i32 m0, s6, 0x10400
	s_nop 0
	global_load_lds_dwordx4 v[40:41], off
	v_lshl_add_u64 v[30:31], v[30:31], 0, vcc
	v_lshl_add_u64 v[32:33], v[32:33], 0, vcc
	v_lshl_add_u64 v[34:35], v[34:35], 0, vcc
	v_lshl_add_u64 v[36:37], v[36:37], 0, vcc
	v_lshl_add_u64 v[38:39], v[38:39], 0, vcc
	v_lshl_add_u64 v[40:41], v[40:41], 0, vcc
	s_add_i32 m0, s5, 0x14000
	s_nop 0
	global_load_lds_dwordx4 v[30:31], off
	s_add_i32 m0, s5, 0x14400
	s_nop 0
	global_load_lds_dwordx4 v[32:33], off
	s_add_i32 m0, s5, 0x14800
	s_nop 0
	global_load_lds_dwordx4 v[34:35], off
	s_add_i32 m0, s5, 0x14c00
	s_nop 0
	global_load_lds_dwordx4 v[36:37], off
	s_add_i32 m0, s6, 0x1c000
	s_nop 0
	global_load_lds_dwordx4 v[38:39], off
	s_add_i32 m0, s6, 0x1c400
	s_nop 0
	global_load_lds_dwordx4 v[40:41], off
	v_lshl_add_u64 v[30:31], v[30:31], 0, vcc
	v_lshl_add_u64 v[32:33], v[32:33], 0, vcc
	v_lshl_add_u64 v[34:35], v[34:35], 0, vcc
	v_lshl_add_u64 v[36:37], v[36:37], 0, vcc
	v_lshl_add_u64 v[38:39], v[38:39], 0, vcc
	v_lshl_add_u64 v[40:41], v[40:41], 0, vcc
	s_waitcnt vmcnt(6)
	s_barrier
	ds_read_b128 v[46:49], v42
	ds_read_b128 v[78:81], v43
	v_xor_b32_e32 v44, 16, v42
	v_xor_b32_e32 v45, 16, v43
	ds_read_b128 v[50:53], v44
	ds_read_b128 v[82:85], v45
	v_xor_b32_e32 v44, 32, v42
	v_xor_b32_e32 v45, 32, v43
	ds_read_b128 v[54:57], v44
	ds_read_b128 v[86:89], v45
	v_xor_b32_e32 v44, 48, v42
	v_xor_b32_e32 v45, 48, v43
	ds_read_b128 v[58:61], v44
	ds_read_b128 v[90:93], v45
	v_xor_b32_e32 v44, 64, v42
	v_xor_b32_e32 v45, 64, v43
	ds_read_b128 v[62:65], v44
	ds_read_b128 v[94:97], v45
	v_xor_b32_e32 v44, 0x50, v42
	v_xor_b32_e32 v45, 0x50, v43
	ds_read_b128 v[66:69], v44
	ds_read_b128 v[98:101], v45
	v_xor_b32_e32 v44, 0x60, v42
	v_xor_b32_e32 v45, 0x60, v43
	ds_read_b128 v[70:73], v44
	ds_read_b128 v[102:105], v45
	v_xor_b32_e32 v44, 0x70, v42
	v_xor_b32_e32 v45, 0x70, v43
	ds_read_b128 v[74:77], v44
	ds_read_b128 v[106:109], v45
	s_waitcnt lgkmcnt(0)
	s_barrier
; __device__ __forceinline__ void phase_row1(const Frame& F, int l) {
;     ...
; #pragma unroll 16
;             for (int s4 = 0; s4 < 256; s4 += 4) { const f32x4 a = *(const f32x4*)(wp + s4), bq = *(const f32x4*)(hp + s4);
;                 c = __builtin_amdgcn_mfma_f32_16x16x4f32(a.x, bq.x, c, 0, 0, 0); c = __builtin_amdgcn_mfma_f32_16x16x4f32(a.y, bq.y, c, 0, 0, 0);
;                 c = __builtin_amdgcn_mfma_f32_16x16x4f32(a.z, bq.z, c, 0, 0, 0); c = __builtin_amdgcn_mfma_f32_16x16x4f32(a.w, bq.w, c, 0, 0, 0); }
	s_add_i32 m0, s5, 0x8000
	s_nop 0
	global_load_lds_dwordx4 v[30:31], off
	s_add_i32 m0, s5, 0x8400
	s_nop 0
	global_load_lds_dwordx4 v[32:33], off
	s_add_i32 m0, s5, 0x8800
	s_nop 0
	global_load_lds_dwordx4 v[34:35], off
	s_add_i32 m0, s5, 0x8c00
	s_nop 0
	global_load_lds_dwordx4 v[36:37], off
	s_add_i32 m0, s6, 0x10000
	s_nop 0
	global_load_lds_dwordx4 v[38:39], off
	s_add_i32 m0, s6, 0x10400
	s_nop 0
	global_load_lds_dwordx4 v[40:41], off
	v_lshl_add_u64 v[30:31], v[30:31], 0, vcc
	v_lshl_add_u64 v[32:33], v[32:33], 0, vcc
	v_lshl_add_u64 v[34:35], v[34:35], 0, vcc
	v_lshl_add_u64 v[36:37], v[36:37], 0, vcc
	v_lshl_add_u64 v[38:39], v[38:39], 0, vcc
	v_lshl_add_u64 v[40:41], v[40:41], 0, vcc
	v_mfma_f32_16x16x4_f32 v[18:21], v78, v46, v[18:21]
	v_mfma_f32_16x16x4_f32 v[18:21], v79, v47, v[18:21]
	v_mfma_f32_16x16x4_f32 v[18:21], v80, v48, v[18:21]
	v_mfma_f32_16x16x4_f32 v[18:21], v81, v49, v[18:21]
	v_mfma_f32_16x16x4_f32 v[18:21], v82, v50, v[18:21]
	v_mfma_f32_16x16x4_f32 v[18:21], v83, v51, v[18:21]
	v_mfma_f32_16x16x4_f32 v[18:21], v84, v52, v[18:21]
	v_mfma_f32_16x16x4_f32 v[18:21], v85, v53, v[18:21]
	v_mfma_f32_16x16x4_f32 v[18:21], v86, v54, v[18:21]
	v_mfma_f32_16x16x4_f32 v[18:21], v87, v55, v[18:21]
	v_mfma_f32_16x16x4_f32 v[18:21], v88, v56, v[18:21]
	v_mfma_f32_16x16x4_f32 v[18:21], v89, v57, v[18:21]
	v_mfma_f32_16x16x4_f32 v[18:21], v90, v58, v[18:21]
	v_mfma_f32_16x16x4_f32 v[18:21], v91, v59, v[18:21]
	v_mfma_f32_16x16x4_f32 v[18:21], v92, v60, v[18:21]
	v_mfma_f32_16x16x4_f32 v[18:21], v93, v61, v[18:21]
	v_mfma_f32_16x16x4_f32 v[18:21], v94, v62, v[18:21]
	v_mfma_f32_16x16x4_f32 v[18:21], v95, v63, v[18:21]
	v_mfma_f32_16x16x4_f32 v[18:21], v96, v64, v[18:21]
	v_mfma_f32_16x16x4_f32 v[18:21], v97, v65, v[18:21]
	v_mfma_f32_16x16x4_f32 v[18:21], v98, v66, v[18:21]
	v_mfma_f32_16x16x4_f32 v[18:21], v99, v67, v[18:21]
	v_mfma_f32_16x16x4_f32 v[18:21], v100, v68, v[18:21]
	v_mfma_f32_16x16x4_f32 v[18:21], v101, v69, v[18:21]
	v_mfma_f32_16x16x4_f32 v[18:21], v102, v70, v[18:21]
	v_mfma_f32_16x16x4_f32 v[18:21], v103, v71, v[18:21]
	v_mfma_f32_16x16x4_f32 v[18:21], v104, v72, v[18:21]
	v_mfma_f32_16x16x4_f32 v[18:21], v105, v73, v[18:21]
	v_mfma_f32_16x16x4_f32 v[18:21], v106, v74, v[18:21]
	v_mfma_f32_16x16x4_f32 v[18:21], v107, v75, v[18:21]
	v_mfma_f32_16x16x4_f32 v[18:21], v108, v76, v[18:21]
	v_mfma_f32_16x16x4_f32 v[18:21], v109, v77, v[18:21]
	s_waitcnt vmcnt(6)
	s_barrier
	ds_read_b128 v[46:49], v42 offset:49152
	ds_read_b128 v[78:81], v43 offset:49152
	v_xor_b32_e32 v44, 16, v42
	v_xor_b32_e32 v45, 16, v43
	ds_read_b128 v[50:53], v44 offset:49152
	ds_read_b128 v[82:85], v45 offset:49152
	v_xor_b32_e32 v44, 32, v42
	v_xor_b32_e32 v45, 32, v43
	ds_read_b128 v[54:57], v44 offset:49152
	ds_read_b128 v[86:89], v45 offset:49152
	v_xor_b32_e32 v44, 48, v42
	v_xor_b32_e32 v45, 48, v43
	ds_read_b128 v[58:61], v44 offset:49152
	ds_read_b128 v[90:93], v45 offset:49152
	v_xor_b32_e32 v44, 64, v42
	v_xor_b32_e32 v45, 64, v43
	ds_read_b128 v[62:65], v44 offset:49152
	ds_read_b128 v[94:97], v45 offset:49152
	v_xor_b32_e32 v44, 0x50, v42
	v_xor_b32_e32 v45, 0x50, v43
	ds_read_b128 v[66:69], v44 offset:49152
	ds_read_b128 v[98:101], v45 offset:49152
	v_xor_b32_e32 v44, 0x60, v42
	v_xor_b32_e32 v45, 0x60, v43
	ds_read_b128 v[70:73], v44 offset:49152
	ds_read_b128 v[102:105], v45 offset:49152
	v_xor_b32_e32 v44, 0x70, v42
	v_xor_b32_e32 v45, 0x70, v43
	ds_read_b128 v[74:77], v44 offset:49152
	ds_read_b128 v[106:109], v45 offset:49152
	s_waitcnt lgkmcnt(0)
	s_barrier
	s_add_i32 m0, s5, 0x14000
	s_nop 0
	global_load_lds_dwordx4 v[30:31], off
	s_add_i32 m0, s5, 0x14400
	s_nop 0
	global_load_lds_dwordx4 v[32:33], off
	s_add_i32 m0, s5, 0x14800
	s_nop 0
	global_load_lds_dwordx4 v[34:35], off
	s_add_i32 m0, s5, 0x14c00
	s_nop 0
	global_load_lds_dwordx4 v[36:37], off
	s_add_i32 m0, s6, 0x1c000
	s_nop 0
	global_load_lds_dwordx4 v[38:39], off
	s_add_i32 m0, s6, 0x1c400
	s_nop 0
	global_load_lds_dwordx4 v[40:41], off
	v_lshl_add_u64 v[30:31], v[30:31], 0, vcc
	v_lshl_add_u64 v[32:33], v[32:33], 0, vcc
	v_lshl_add_u64 v[34:35], v[34:35], 0, vcc
	v_lshl_add_u64 v[36:37], v[36:37], 0, vcc
	v_lshl_add_u64 v[38:39], v[38:39], 0, vcc
	v_lshl_add_u64 v[40:41], v[40:41], 0, vcc
	v_mfma_f32_16x16x4_f32 v[18:21], v78, v46, v[18:21]
	v_mfma_f32_16x16x4_f32 v[18:21], v79, v47, v[18:21]
	v_mfma_f32_16x16x4_f32 v[18:21], v80, v48, v[18:21]
	v_mfma_f32_16x16x4_f32 v[18:21], v81, v49, v[18:21]
	v_mfma_f32_16x16x4_f32 v[18:21], v82, v50, v[18:21]
	v_mfma_f32_16x16x4_f32 v[18:21], v83, v51, v[18:21]
	v_mfma_f32_16x16x4_f32 v[18:21], v84, v52, v[18:21]
	v_mfma_f32_16x16x4_f32 v[18:21], v85, v53, v[18:21]
	v_mfma_f32_16x16x4_f32 v[18:21], v86, v54, v[18:21]
	v_mfma_f32_16x16x4_f32 v[18:21], v87, v55, v[18:21]
	v_mfma_f32_16x16x4_f32 v[18:21], v88, v56, v[18:21]
	v_mfma_f32_16x16x4_f32 v[18:21], v89, v57, v[18:21]
	v_mfma_f32_16x16x4_f32 v[18:21], v90, v58, v[18:21]
	v_mfma_f32_16x16x4_f32 v[18:21], v91, v59, v[18:21]
	v_mfma_f32_16x16x4_f32 v[18:21], v92, v60, v[18:21]
	v_mfma_f32_16x16x4_f32 v[18:21], v93, v61, v[18:21]
	v_mfma_f32_16x16x4_f32 v[18:21], v94, v62, v[18:21]
	v_mfma_f32_16x16x4_f32 v[18:21], v95, v63, v[18:21]
	v_mfma_f32_16x16x4_f32 v[18:21], v96, v64, v[18:21]
	v_mfma_f32_16x16x4_f32 v[18:21], v97, v65, v[18:21]
	v_mfma_f32_16x16x4_f32 v[18:21], v98, v66, v[18:21]
	v_mfma_f32_16x16x4_f32 v[18:21], v99, v67, v[18:21]
	v_mfma_f32_16x16x4_f32 v[18:21], v100, v68, v[18:21]
	v_mfma_f32_16x16x4_f32 v[18:21], v101, v69, v[18:21]
	v_mfma_f32_16x16x4_f32 v[18:21], v102, v70, v[18:21]
	v_mfma_f32_16x16x4_f32 v[18:21], v103, v71, v[18:21]
	v_mfma_f32_16x16x4_f32 v[18:21], v104, v72, v[18:21]
	v_mfma_f32_16x16x4_f32 v[18:21], v105, v73, v[18:21]
	v_mfma_f32_16x16x4_f32 v[18:21], v106, v74, v[18:21]
	v_mfma_f32_16x16x4_f32 v[18:21], v107, v75, v[18:21]
	v_mfma_f32_16x16x4_f32 v[18:21], v108, v76, v[18:21]
	v_mfma_f32_16x16x4_f32 v[18:21], v109, v77, v[18:21]
	s_waitcnt vmcnt(6)
	s_barrier
; __device__ __forceinline__ void phase_row1(const Frame& F, int l) {
;     ...
; #pragma unroll 16
;             for (int s4 = 0; s4 < 256; s4 += 4) { const f32x4 a = *(const f32x4*)(wp + s4), bq = *(const f32x4*)(hp + s4);
;                 c = __builtin_amdgcn_mfma_f32_16x16x4f32(a.x, bq.x, c, 0, 0, 0); c = __builtin_amdgcn_mfma_f32_16x16x4f32(a.y, bq.y, c, 0, 0, 0);
;                 c = __builtin_amdgcn_mfma_f32_16x16x4f32(a.z, bq.z, c, 0, 0, 0); c = __builtin_amdgcn_mfma_f32_16x16x4f32(a.w, bq.w, c, 0, 0, 0); }
	ds_read_b128 v[46:49], v42
	ds_read_b128 v[78:81], v43
	v_xor_b32_e32 v44, 16, v42
	v_xor_b32_e32 v45, 16, v43
	ds_read_b128 v[50:53], v44
	ds_read_b128 v[82:85], v45
	v_xor_b32_e32 v44, 32, v42
	v_xor_b32_e32 v45, 32, v43
	ds_read_b128 v[54:57], v44
	ds_read_b128 v[86:89], v45
	v_xor_b32_e32 v44, 48, v42
	v_xor_b32_e32 v45, 48, v43
	ds_read_b128 v[58:61], v44
	ds_read_b128 v[90:93], v45
	v_xor_b32_e32 v44, 64, v42
	v_xor_b32_e32 v45, 64, v43
	ds_read_b128 v[62:65], v44
	ds_read_b128 v[94:97], v45
	v_xor_b32_e32 v44, 0x50, v42
	v_xor_b32_e32 v45, 0x50, v43
	ds_read_b128 v[66:69], v44
	ds_read_b128 v[98:101], v45
	v_xor_b32_e32 v44, 0x60, v42
	v_xor_b32_e32 v45, 0x60, v43
	ds_read_b128 v[70:73], v44
	ds_read_b128 v[102:105], v45
	v_xor_b32_e32 v44, 0x70, v42
	v_xor_b32_e32 v45, 0x70, v43
	ds_read_b128 v[74:77], v44
	ds_read_b128 v[106:109], v45
	s_waitcnt lgkmcnt(0)
	s_barrier
	s_add_i32 m0, s5, 0x8000
	s_nop 0
	global_load_lds_dwordx4 v[30:31], off
	s_add_i32 m0, s5, 0x8400
	s_nop 0
	global_load_lds_dwordx4 v[32:33], off
	s_add_i32 m0, s5, 0x8800
	s_nop 0
	global_load_lds_dwordx4 v[34:35], off
	s_add_i32 m0, s5, 0x8c00
	s_nop 0
	global_load_lds_dwordx4 v[36:37], off
	s_add_i32 m0, s6, 0x10000
	s_nop 0
	global_load_lds_dwordx4 v[38:39], off
	s_add_i32 m0, s6, 0x10400
	s_nop 0
	global_load_lds_dwordx4 v[40:41], off
	v_lshl_add_u64 v[30:31], v[30:31], 0, vcc
	v_lshl_add_u64 v[32:33], v[32:33], 0, vcc
	v_lshl_add_u64 v[34:35], v[34:35], 0, vcc
	v_lshl_add_u64 v[36:37], v[36:37], 0, vcc
	v_lshl_add_u64 v[38:39], v[38:39], 0, vcc
	v_lshl_add_u64 v[40:41], v[40:41], 0, vcc
	v_mfma_f32_16x16x4_f32 v[18:21], v78, v46, v[18:21]
	v_mfma_f32_16x16x4_f32 v[18:21], v79, v47, v[18:21]
	v_mfma_f32_16x16x4_f32 v[18:21], v80, v48, v[18:21]
	v_mfma_f32_16x16x4_f32 v[18:21], v81, v49, v[18:21]
	v_mfma_f32_16x16x4_f32 v[18:21], v82, v50, v[18:21]
	v_mfma_f32_16x16x4_f32 v[18:21], v83, v51, v[18:21]
	v_mfma_f32_16x16x4_f32 v[18:21], v84, v52, v[18:21]
	v_mfma_f32_16x16x4_f32 v[18:21], v85, v53, v[18:21]
	v_mfma_f32_16x16x4_f32 v[18:21], v86, v54, v[18:21]
	v_mfma_f32_16x16x4_f32 v[18:21], v87, v55, v[18:21]
	v_mfma_f32_16x16x4_f32 v[18:21], v88, v56, v[18:21]
	v_mfma_f32_16x16x4_f32 v[18:21], v89, v57, v[18:21]
	v_mfma_f32_16x16x4_f32 v[18:21], v90, v58, v[18:21]
	v_mfma_f32_16x16x4_f32 v[18:21], v91, v59, v[18:21]
	v_mfma_f32_16x16x4_f32 v[18:21], v92, v60, v[18:21]
	v_mfma_f32_16x16x4_f32 v[18:21], v93, v61, v[18:21]
	v_mfma_f32_16x16x4_f32 v[18:21], v94, v62, v[18:21]
	v_mfma_f32_16x16x4_f32 v[18:21], v95, v63, v[18:21]
	v_mfma_f32_16x16x4_f32 v[18:21], v96, v64, v[18:21]
	v_mfma_f32_16x16x4_f32 v[18:21], v97, v65, v[18:21]
	v_mfma_f32_16x16x4_f32 v[18:21], v98, v66, v[18:21]
	v_mfma_f32_16x16x4_f32 v[18:21], v99, v67, v[18:21]
	v_mfma_f32_16x16x4_f32 v[18:21], v100, v68, v[18:21]
	v_mfma_f32_16x16x4_f32 v[18:21], v101, v69, v[18:21]
	v_mfma_f32_16x16x4_f32 v[18:21], v102, v70, v[18:21]
	v_mfma_f32_16x16x4_f32 v[18:21], v103, v71, v[18:21]
	v_mfma_f32_16x16x4_f32 v[18:21], v104, v72, v[18:21]
	v_mfma_f32_16x16x4_f32 v[18:21], v105, v73, v[18:21]
	v_mfma_f32_16x16x4_f32 v[18:21], v106, v74, v[18:21]
	v_mfma_f32_16x16x4_f32 v[18:21], v107, v75, v[18:21]
	v_mfma_f32_16x16x4_f32 v[18:21], v108, v76, v[18:21]
	v_mfma_f32_16x16x4_f32 v[18:21], v109, v77, v[18:21]
	s_waitcnt vmcnt(6)
	s_barrier
	ds_read_b128 v[46:49], v42 offset:49152
	ds_read_b128 v[78:81], v43 offset:49152
	v_xor_b32_e32 v44, 16, v42
	v_xor_b32_e32 v45, 16, v43
	ds_read_b128 v[50:53], v44 offset:49152
	ds_read_b128 v[82:85], v45 offset:49152
	v_xor_b32_e32 v44, 32, v42
	v_xor_b32_e32 v45, 32, v43
	ds_read_b128 v[54:57], v44 offset:49152
	ds_read_b128 v[86:89], v45 offset:49152
	v_xor_b32_e32 v44, 48, v42
	v_xor_b32_e32 v45, 48, v43
	ds_read_b128 v[58:61], v44 offset:49152
	ds_read_b128 v[90:93], v45 offset:49152
	v_xor_b32_e32 v44, 64, v42
	v_xor_b32_e32 v45, 64, v43
	ds_read_b128 v[62:65], v44 offset:49152
	ds_read_b128 v[94:97], v45 offset:49152
	v_xor_b32_e32 v44, 0x50, v42
	v_xor_b32_e32 v45, 0x50, v43
	ds_read_b128 v[66:69], v44 offset:49152
	ds_read_b128 v[98:101], v45 offset:49152
	v_xor_b32_e32 v44, 0x60, v42
	v_xor_b32_e32 v45, 0x60, v43
	ds_read_b128 v[70:73], v44 offset:49152
	ds_read_b128 v[102:105], v45 offset:49152
	v_xor_b32_e32 v44, 0x70, v42
	v_xor_b32_e32 v45, 0x70, v43
	ds_read_b128 v[74:77], v44 offset:49152
	ds_read_b128 v[106:109], v45 offset:49152
	s_waitcnt lgkmcnt(0)
	s_barrier
; __device__ __forceinline__ void phase_row1(const Frame& F, int l) {
;     ...
; #pragma unroll 16
;             for (int s4 = 0; s4 < 256; s4 += 4) { const f32x4 a = *(const f32x4*)(wp + s4), bq = *(const f32x4*)(hp + s4);
;                 c = __builtin_amdgcn_mfma_f32_16x16x4f32(a.x, bq.x, c, 0, 0, 0); c = __builtin_amdgcn_mfma_f32_16x16x4f32(a.y, bq.y, c, 0, 0, 0);
;                 c = __builtin_amdgcn_mfma_f32_16x16x4f32(a.z, bq.z, c, 0, 0, 0); c = __builtin_amdgcn_mfma_f32_16x16x4f32(a.w, bq.w, c, 0, 0, 0); }
	s_add_i32 m0, s5, 0x14000
	s_nop 0
	global_load_lds_dwordx4 v[30:31], off
	s_add_i32 m0, s5, 0x14400
	s_nop 0
	global_load_lds_dwordx4 v[32:33], off
	s_add_i32 m0, s5, 0x14800
	s_nop 0
	global_load_lds_dwordx4 v[34:35], off
	s_add_i32 m0, s5, 0x14c00
	s_nop 0
	global_load_lds_dwordx4 v[36:37], off
	s_add_i32 m0, s6, 0x1c000
	s_nop 0
	global_load_lds_dwordx4 v[38:39], off
	s_add_i32 m0, s6, 0x1c400
	s_nop 0
	global_load_lds_dwordx4 v[40:41], off
	v_lshl_add_u64 v[30:31], v[30:31], 0, vcc
	v_lshl_add_u64 v[32:33], v[32:33], 0, vcc
	v_lshl_add_u64 v[34:35], v[34:35], 0, vcc
	v_lshl_add_u64 v[36:37], v[36:37], 0, vcc
	v_lshl_add_u64 v[38:39], v[38:39], 0, vcc
	v_lshl_add_u64 v[40:41], v[40:41], 0, vcc
	v_mfma_f32_16x16x4_f32 v[18:21], v78, v46, v[18:21]
	v_mfma_f32_16x16x4_f32 v[18:21], v79, v47, v[18:21]
	v_mfma_f32_16x16x4_f32 v[18:21], v80, v48, v[18:21]
	v_mfma_f32_16x16x4_f32 v[18:21], v81, v49, v[18:21]
	v_mfma_f32_16x16x4_f32 v[18:21], v82, v50, v[18:21]
	v_mfma_f32_16x16x4_f32 v[18:21], v83, v51, v[18:21]
	v_mfma_f32_16x16x4_f32 v[18:21], v84, v52, v[18:21]
	v_mfma_f32_16x16x4_f32 v[18:21], v85, v53, v[18:21]
	v_mfma_f32_16x16x4_f32 v[18:21], v86, v54, v[18:21]
	v_mfma_f32_16x16x4_f32 v[18:21], v87, v55, v[18:21]
	v_mfma_f32_16x16x4_f32 v[18:21], v88, v56, v[18:21]
	v_mfma_f32_16x16x4_f32 v[18:21], v89, v57, v[18:21]
	v_mfma_f32_16x16x4_f32 v[18:21], v90, v58, v[18:21]
	v_mfma_f32_16x16x4_f32 v[18:21], v91, v59, v[18:21]
	v_mfma_f32_16x16x4_f32 v[18:21], v92, v60, v[18:21]
	v_mfma_f32_16x16x4_f32 v[18:21], v93, v61, v[18:21]
	v_mfma_f32_16x16x4_f32 v[18:21], v94, v62, v[18:21]
	v_mfma_f32_16x16x4_f32 v[18:21], v95, v63, v[18:21]
	v_mfma_f32_16x16x4_f32 v[18:21], v96, v64, v[18:21]
	v_mfma_f32_16x16x4_f32 v[18:21], v97, v65, v[18:21]
	v_mfma_f32_16x16x4_f32 v[18:21], v98, v66, v[18:21]
	v_mfma_f32_16x16x4_f32 v[18:21], v99, v67, v[18:21]
	v_mfma_f32_16x16x4_f32 v[18:21], v100, v68, v[18:21]
	v_mfma_f32_16x16x4_f32 v[18:21], v101, v69, v[18:21]
	v_mfma_f32_16x16x4_f32 v[18:21], v102, v70, v[18:21]
	v_mfma_f32_16x16x4_f32 v[18:21], v103, v71, v[18:21]
	v_mfma_f32_16x16x4_f32 v[18:21], v104, v72, v[18:21]
	v_mfma_f32_16x16x4_f32 v[18:21], v105, v73, v[18:21]
	v_mfma_f32_16x16x4_f32 v[18:21], v106, v74, v[18:21]
	v_mfma_f32_16x16x4_f32 v[18:21], v107, v75, v[18:21]
	v_mfma_f32_16x16x4_f32 v[18:21], v108, v76, v[18:21]
	v_mfma_f32_16x16x4_f32 v[18:21], v109, v77, v[18:21]
	s_waitcnt vmcnt(6)
	s_barrier
	ds_read_b128 v[46:49], v42
	ds_read_b128 v[78:81], v43
	v_xor_b32_e32 v44, 16, v42
	v_xor_b32_e32 v45, 16, v43
	ds_read_b128 v[50:53], v44
	ds_read_b128 v[82:85], v45
	v_xor_b32_e32 v44, 32, v42
	v_xor_b32_e32 v45, 32, v43
	ds_read_b128 v[54:57], v44
	ds_read_b128 v[86:89], v45
	v_xor_b32_e32 v44, 48, v42
	v_xor_b32_e32 v45, 48, v43
	ds_read_b128 v[58:61], v44
	ds_read_b128 v[90:93], v45
	v_xor_b32_e32 v44, 64, v42
	v_xor_b32_e32 v45, 64, v43
	ds_read_b128 v[62:65], v44
	ds_read_b128 v[94:97], v45
	v_xor_b32_e32 v44, 0x50, v42
	v_xor_b32_e32 v45, 0x50, v43
	ds_read_b128 v[66:69], v44
	ds_read_b128 v[98:101], v45
	v_xor_b32_e32 v44, 0x60, v42
	v_xor_b32_e32 v45, 0x60, v43
	ds_read_b128 v[70:73], v44
	ds_read_b128 v[102:105], v45
	v_xor_b32_e32 v44, 0x70, v42
	v_xor_b32_e32 v45, 0x70, v43
	ds_read_b128 v[74:77], v44
	ds_read_b128 v[106:109], v45
	s_waitcnt lgkmcnt(0)
	s_barrier
	s_add_i32 m0, s5, 0x8000
	s_nop 0
	global_load_lds_dwordx4 v[30:31], off
	s_add_i32 m0, s5, 0x8400
	s_nop 0
	global_load_lds_dwordx4 v[32:33], off
	s_add_i32 m0, s5, 0x8800
	s_nop 0
	global_load_lds_dwordx4 v[34:35], off
	s_add_i32 m0, s5, 0x8c00
	s_nop 0
	global_load_lds_dwordx4 v[36:37], off
	s_add_i32 m0, s6, 0x10000
	s_nop 0
	global_load_lds_dwordx4 v[38:39], off
	s_add_i32 m0, s6, 0x10400
	s_nop 0
	global_load_lds_dwordx4 v[40:41], off
	v_lshl_add_u64 v[30:31], v[30:31], 0, vcc
	v_lshl_add_u64 v[32:33], v[32:33], 0, vcc
	v_lshl_add_u64 v[34:35], v[34:35], 0, vcc
	v_lshl_add_u64 v[36:37], v[36:37], 0, vcc
	v_lshl_add_u64 v[38:39], v[38:39], 0, vcc
	v_lshl_add_u64 v[40:41], v[40:41], 0, vcc
	v_mfma_f32_16x16x4_f32 v[18:21], v78, v46, v[18:21]
	v_mfma_f32_16x16x4_f32 v[18:21], v79, v47, v[18:21]
	v_mfma_f32_16x16x4_f32 v[18:21], v80, v48, v[18:21]
	v_mfma_f32_16x16x4_f32 v[18:21], v81, v49, v[18:21]
	v_mfma_f32_16x16x4_f32 v[18:21], v82, v50, v[18:21]
	v_mfma_f32_16x16x4_f32 v[18:21], v83, v51, v[18:21]
	v_mfma_f32_16x16x4_f32 v[18:21], v84, v52, v[18:21]
	v_mfma_f32_16x16x4_f32 v[18:21], v85, v53, v[18:21]
	v_mfma_f32_16x16x4_f32 v[18:21], v86, v54, v[18:21]
	v_mfma_f32_16x16x4_f32 v[18:21], v87, v55, v[18:21]
	v_mfma_f32_16x16x4_f32 v[18:21], v88, v56, v[18:21]
	v_mfma_f32_16x16x4_f32 v[18:21], v89, v57, v[18:21]
	v_mfma_f32_16x16x4_f32 v[18:21], v90, v58, v[18:21]
	v_mfma_f32_16x16x4_f32 v[18:21], v91, v59, v[18:21]
	v_mfma_f32_16x16x4_f32 v[18:21], v92, v60, v[18:21]
	v_mfma_f32_16x16x4_f32 v[18:21], v93, v61, v[18:21]
	v_mfma_f32_16x16x4_f32 v[18:21], v94, v62, v[18:21]
	v_mfma_f32_16x16x4_f32 v[18:21], v95, v63, v[18:21]
	v_mfma_f32_16x16x4_f32 v[18:21], v96, v64, v[18:21]
	v_mfma_f32_16x16x4_f32 v[18:21], v97, v65, v[18:21]
	v_mfma_f32_16x16x4_f32 v[18:21], v98, v66, v[18:21]
	v_mfma_f32_16x16x4_f32 v[18:21], v99, v67, v[18:21]
	v_mfma_f32_16x16x4_f32 v[18:21], v100, v68, v[18:21]
	v_mfma_f32_16x16x4_f32 v[18:21], v101, v69, v[18:21]
	v_mfma_f32_16x16x4_f32 v[18:21], v102, v70, v[18:21]
	v_mfma_f32_16x16x4_f32 v[18:21], v103, v71, v[18:21]
	v_mfma_f32_16x16x4_f32 v[18:21], v104, v72, v[18:21]
	v_mfma_f32_16x16x4_f32 v[18:21], v105, v73, v[18:21]
	v_mfma_f32_16x16x4_f32 v[18:21], v106, v74, v[18:21]
	v_mfma_f32_16x16x4_f32 v[18:21], v107, v75, v[18:21]
	v_mfma_f32_16x16x4_f32 v[18:21], v108, v76, v[18:21]
	v_mfma_f32_16x16x4_f32 v[18:21], v109, v77, v[18:21]
	s_waitcnt vmcnt(6)
	s_barrier
; __device__ __forceinline__ void phase_row1(const Frame& F, int l) {
;     ...
; #pragma unroll 16
;             for (int s4 = 0; s4 < 256; s4 += 4) { const f32x4 a = *(const f32x4*)(wp + s4), bq = *(const f32x4*)(hp + s4);
;                 c = __builtin_amdgcn_mfma_f32_16x16x4f32(a.x, bq.x, c, 0, 0, 0); c = __builtin_amdgcn_mfma_f32_16x16x4f32(a.y, bq.y, c, 0, 0, 0);
;                 c = __builtin_amdgcn_mfma_f32_16x16x4f32(a.z, bq.z, c, 0, 0, 0); c = __builtin_amdgcn_mfma_f32_16x16x4f32(a.w, bq.w, c, 0, 0, 0); }
	ds_read_b128 v[46:49], v42 offset:49152
	ds_read_b128 v[78:81], v43 offset:49152
	v_xor_b32_e32 v44, 16, v42
	v_xor_b32_e32 v45, 16, v43
	ds_read_b128 v[50:53], v44 offset:49152
	ds_read_b128 v[82:85], v45 offset:49152
	v_xor_b32_e32 v44, 32, v42
	v_xor_b32_e32 v45, 32, v43
	ds_read_b128 v[54:57], v44 offset:49152
	ds_read_b128 v[86:89], v45 offset:49152
	v_xor_b32_e32 v44, 48, v42
	v_xor_b32_e32 v45, 48, v43
	ds_read_b128 v[58:61], v44 offset:49152
	ds_read_b128 v[90:93], v45 offset:49152
	v_xor_b32_e32 v44, 64, v42
	v_xor_b32_e32 v45, 64, v43
	ds_read_b128 v[62:65], v44 offset:49152
	ds_read_b128 v[94:97], v45 offset:49152
	v_xor_b32_e32 v44, 0x50, v42
	v_xor_b32_e32 v45, 0x50, v43
	ds_read_b128 v[66:69], v44 offset:49152
	ds_read_b128 v[98:101], v45 offset:49152
	v_xor_b32_e32 v44, 0x60, v42
	v_xor_b32_e32 v45, 0x60, v43
	ds_read_b128 v[70:73], v44 offset:49152
	ds_read_b128 v[102:105], v45 offset:49152
	v_xor_b32_e32 v44, 0x70, v42
	v_xor_b32_e32 v45, 0x70, v43
	ds_read_b128 v[74:77], v44 offset:49152
	ds_read_b128 v[106:109], v45 offset:49152
	s_waitcnt lgkmcnt(0)
	s_barrier
	s_add_i32 m0, s5, 0x14000
	s_nop 0
	global_load_lds_dwordx4 v[30:31], off
	s_add_i32 m0, s5, 0x14400
	s_nop 0
	global_load_lds_dwordx4 v[32:33], off
	s_add_i32 m0, s5, 0x14800
	s_nop 0
	global_load_lds_dwordx4 v[34:35], off
	s_add_i32 m0, s5, 0x14c00
	s_nop 0
	global_load_lds_dwordx4 v[36:37], off
	s_add_i32 m0, s6, 0x1c000
	s_nop 0
	global_load_lds_dwordx4 v[38:39], off
	s_add_i32 m0, s6, 0x1c400
	s_nop 0
	global_load_lds_dwordx4 v[40:41], off
	v_lshl_add_u64 v[30:31], v[30:31], 0, vcc
	v_lshl_add_u64 v[32:33], v[32:33], 0, vcc
	v_lshl_add_u64 v[34:35], v[34:35], 0, vcc
	v_lshl_add_u64 v[36:37], v[36:37], 0, vcc
	v_lshl_add_u64 v[38:39], v[38:39], 0, vcc
	v_lshl_add_u64 v[40:41], v[40:41], 0, vcc
	v_mfma_f32_16x16x4_f32 v[18:21], v78, v46, v[18:21]
	v_mfma_f32_16x16x4_f32 v[18:21], v79, v47, v[18:21]
	v_mfma_f32_16x16x4_f32 v[18:21], v80, v48, v[18:21]
	v_mfma_f32_16x16x4_f32 v[18:21], v81, v49, v[18:21]
	v_mfma_f32_16x16x4_f32 v[18:21], v82, v50, v[18:21]
	v_mfma_f32_16x16x4_f32 v[18:21], v83, v51, v[18:21]
	v_mfma_f32_16x16x4_f32 v[18:21], v84, v52, v[18:21]
	v_mfma_f32_16x16x4_f32 v[18:21], v85, v53, v[18:21]
	v_mfma_f32_16x16x4_f32 v[18:21], v86, v54, v[18:21]
	v_mfma_f32_16x16x4_f32 v[18:21], v87, v55, v[18:21]
	v_mfma_f32_16x16x4_f32 v[18:21], v88, v56, v[18:21]
	v_mfma_f32_16x16x4_f32 v[18:21], v89, v57, v[18:21]
	v_mfma_f32_16x16x4_f32 v[18:21], v90, v58, v[18:21]
	v_mfma_f32_16x16x4_f32 v[18:21], v91, v59, v[18:21]
	v_mfma_f32_16x16x4_f32 v[18:21], v92, v60, v[18:21]
	v_mfma_f32_16x16x4_f32 v[18:21], v93, v61, v[18:21]
	v_mfma_f32_16x16x4_f32 v[18:21], v94, v62, v[18:21]
	v_mfma_f32_16x16x4_f32 v[18:21], v95, v63, v[18:21]
	v_mfma_f32_16x16x4_f32 v[18:21], v96, v64, v[18:21]
	v_mfma_f32_16x16x4_f32 v[18:21], v97, v65, v[18:21]
	v_mfma_f32_16x16x4_f32 v[18:21], v98, v66, v[18:21]
	v_mfma_f32_16x16x4_f32 v[18:21], v99, v67, v[18:21]
	v_mfma_f32_16x16x4_f32 v[18:21], v100, v68, v[18:21]
	v_mfma_f32_16x16x4_f32 v[18:21], v101, v69, v[18:21]
	v_mfma_f32_16x16x4_f32 v[18:21], v102, v70, v[18:21]
	v_mfma_f32_16x16x4_f32 v[18:21], v103, v71, v[18:21]
	v_mfma_f32_16x16x4_f32 v[18:21], v104, v72, v[18:21]
	v_mfma_f32_16x16x4_f32 v[18:21], v105, v73, v[18:21]
	v_mfma_f32_16x16x4_f32 v[18:21], v106, v74, v[18:21]
	v_mfma_f32_16x16x4_f32 v[18:21], v107, v75, v[18:21]
	v_mfma_f32_16x16x4_f32 v[18:21], v108, v76, v[18:21]
	v_mfma_f32_16x16x4_f32 v[18:21], v109, v77, v[18:21]
	s_waitcnt vmcnt(6)
	s_barrier
	ds_read_b128 v[46:49], v42
	ds_read_b128 v[78:81], v43
	v_xor_b32_e32 v44, 16, v42
	v_xor_b32_e32 v45, 16, v43
	ds_read_b128 v[50:53], v44
	ds_read_b128 v[82:85], v45
	v_xor_b32_e32 v44, 32, v42
	v_xor_b32_e32 v45, 32, v43
	ds_read_b128 v[54:57], v44
	ds_read_b128 v[86:89], v45
	v_xor_b32_e32 v44, 48, v42
	v_xor_b32_e32 v45, 48, v43
	ds_read_b128 v[58:61], v44
	ds_read_b128 v[90:93], v45
	v_xor_b32_e32 v44, 64, v42
	v_xor_b32_e32 v45, 64, v43
	ds_read_b128 v[62:65], v44
	ds_read_b128 v[94:97], v45
	v_xor_b32_e32 v44, 0x50, v42
	v_xor_b32_e32 v45, 0x50, v43
	ds_read_b128 v[66:69], v44
	ds_read_b128 v[98:101], v45
	v_xor_b32_e32 v44, 0x60, v42
	v_xor_b32_e32 v45, 0x60, v43
	ds_read_b128 v[70:73], v44
	ds_read_b128 v[102:105], v45
	v_xor_b32_e32 v44, 0x70, v42
	v_xor_b32_e32 v45, 0x70, v43
	ds_read_b128 v[74:77], v44
	ds_read_b128 v[106:109], v45
	s_waitcnt lgkmcnt(14)
	v_mfma_f32_16x16x4_f32 v[18:21], v78, v46, v[18:21]
	v_mfma_f32_16x16x4_f32 v[18:21], v79, v47, v[18:21]
	v_mfma_f32_16x16x4_f32 v[18:21], v80, v48, v[18:21]
	v_mfma_f32_16x16x4_f32 v[18:21], v81, v49, v[18:21]
	s_waitcnt lgkmcnt(12)
	v_mfma_f32_16x16x4_f32 v[18:21], v82, v50, v[18:21]
	v_mfma_f32_16x16x4_f32 v[18:21], v83, v51, v[18:21]
	v_mfma_f32_16x16x4_f32 v[18:21], v84, v52, v[18:21]
	v_mfma_f32_16x16x4_f32 v[18:21], v85, v53, v[18:21]
	s_waitcnt lgkmcnt(10)
	v_mfma_f32_16x16x4_f32 v[18:21], v86, v54, v[18:21]
	v_mfma_f32_16x16x4_f32 v[18:21], v87, v55, v[18:21]
	v_mfma_f32_16x16x4_f32 v[18:21], v88, v56, v[18:21]
	v_mfma_f32_16x16x4_f32 v[18:21], v89, v57, v[18:21]
	s_waitcnt lgkmcnt(8)
	v_mfma_f32_16x16x4_f32 v[18:21], v90, v58, v[18:21]
	v_mfma_f32_16x16x4_f32 v[18:21], v91, v59, v[18:21]
	v_mfma_f32_16x16x4_f32 v[18:21], v92, v60, v[18:21]
	v_mfma_f32_16x16x4_f32 v[18:21], v93, v61, v[18:21]
	s_waitcnt lgkmcnt(6)
	v_mfma_f32_16x16x4_f32 v[18:21], v94, v62, v[18:21]
	v_mfma_f32_16x16x4_f32 v[18:21], v95, v63, v[18:21]
	v_mfma_f32_16x16x4_f32 v[18:21], v96, v64, v[18:21]
	v_mfma_f32_16x16x4_f32 v[18:21], v97, v65, v[18:21]
	s_waitcnt lgkmcnt(4)
	v_mfma_f32_16x16x4_f32 v[18:21], v98, v66, v[18:21]
	v_mfma_f32_16x16x4_f32 v[18:21], v99, v67, v[18:21]
	v_mfma_f32_16x16x4_f32 v[18:21], v100, v68, v[18:21]
	v_mfma_f32_16x16x4_f32 v[18:21], v101, v69, v[18:21]
	s_waitcnt lgkmcnt(2)
	v_mfma_f32_16x16x4_f32 v[18:21], v102, v70, v[18:21]
	v_mfma_f32_16x16x4_f32 v[18:21], v103, v71, v[18:21]
	v_mfma_f32_16x16x4_f32 v[18:21], v104, v72, v[18:21]
	v_mfma_f32_16x16x4_f32 v[18:21], v105, v73, v[18:21]
	s_waitcnt lgkmcnt(0)
	v_mfma_f32_16x16x4_f32 v[18:21], v106, v74, v[18:21]
	v_mfma_f32_16x16x4_f32 v[18:21], v107, v75, v[18:21]
	v_mfma_f32_16x16x4_f32 v[18:21], v108, v76, v[18:21]
	v_mfma_f32_16x16x4_f32 v[18:21], v109, v77, v[18:21]
	s_waitcnt vmcnt(0)
	s_barrier
; __device__ __forceinline__ void phase_row1(const Frame& F, int l) {
;     ...
; #pragma unroll 16
;             for (int s4 = 0; s4 < 256; s4 += 4) { const f32x4 a = *(const f32x4*)(wp + s4), bq = *(const f32x4*)(hp + s4);
;                 c = __builtin_amdgcn_mfma_f32_16x16x4f32(a.x, bq.x, c, 0, 0, 0); c = __builtin_amdgcn_mfma_f32_16x16x4f32(a.y, bq.y, c, 0, 0, 0);
;                 c = __builtin_amdgcn_mfma_f32_16x16x4f32(a.z, bq.z, c, 0, 0, 0); c = __builtin_amdgcn_mfma_f32_16x16x4f32(a.w, bq.w, c, 0, 0, 0); }
; #pragma unroll
;             for (int j = 0; j < 4; ++j) { const int e = 16 * nt + 4 * fq + j; lg[(16 * tile + fr) * 33 + e] = c[j] + F.in[15][l * NE + e]; }
;         }
;         __syncthreads();
;         if (w == 0) {
;             const int row = chunk * 64 + lane;
;             float v[32];
; #pragma unroll
;             for (int e = 0; e < 32; ++e) v[e] = lg[lane * 33 + e];
;             float tv[4]; int ti[4];
; #pragma unroll
;             for (int r = 0; r < 4; ++r) { float bv = v[0]; int bi = 0;
; #pragma unroll
;                 for (int e = 1; e < 32; ++e) { const bool tk = v[e] > bv; bv = tk ? v[e] : bv; bi = tk ? e : bi; }
;                 tv[r] = bv; ti[r] = bi;
; #pragma unroll
;                 for (int e = 0; e < 32; ++e) v[e] = (e == bi) ? -INFINITY : v[e]; }
	ds_read_b128 v[46:49], v42 offset:49152
	ds_read_b128 v[78:81], v43 offset:49152
	v_xor_b32_e32 v44, 16, v42
	v_xor_b32_e32 v45, 16, v43
	ds_read_b128 v[50:53], v44 offset:49152
	ds_read_b128 v[82:85], v45 offset:49152
	v_xor_b32_e32 v44, 32, v42
	v_xor_b32_e32 v45, 32, v43
	ds_read_b128 v[54:57], v44 offset:49152
	ds_read_b128 v[86:89], v45 offset:49152
	v_xor_b32_e32 v44, 48, v42
	v_xor_b32_e32 v45, 48, v43
	ds_read_b128 v[58:61], v44 offset:49152
	ds_read_b128 v[90:93], v45 offset:49152
	v_xor_b32_e32 v44, 64, v42
	v_xor_b32_e32 v45, 64, v43
	ds_read_b128 v[62:65], v44 offset:49152
	ds_read_b128 v[94:97], v45 offset:49152
	v_xor_b32_e32 v44, 0x50, v42
	v_xor_b32_e32 v45, 0x50, v43
	ds_read_b128 v[66:69], v44 offset:49152
	ds_read_b128 v[98:101], v45 offset:49152
	v_xor_b32_e32 v44, 0x60, v42
	v_xor_b32_e32 v45, 0x60, v43
	ds_read_b128 v[70:73], v44 offset:49152
	ds_read_b128 v[102:105], v45 offset:49152
	v_xor_b32_e32 v44, 0x70, v42
	v_xor_b32_e32 v45, 0x70, v43
	ds_read_b128 v[74:77], v44 offset:49152
	ds_read_b128 v[106:109], v45 offset:49152
	s_waitcnt lgkmcnt(14)
	v_mfma_f32_16x16x4_f32 v[18:21], v78, v46, v[18:21]
	v_mfma_f32_16x16x4_f32 v[18:21], v79, v47, v[18:21]
	v_mfma_f32_16x16x4_f32 v[18:21], v80, v48, v[18:21]
	v_mfma_f32_16x16x4_f32 v[18:21], v81, v49, v[18:21]
	s_waitcnt lgkmcnt(12)
	v_mfma_f32_16x16x4_f32 v[18:21], v82, v50, v[18:21]
	v_mfma_f32_16x16x4_f32 v[18:21], v83, v51, v[18:21]
	v_mfma_f32_16x16x4_f32 v[18:21], v84, v52, v[18:21]
	v_mfma_f32_16x16x4_f32 v[18:21], v85, v53, v[18:21]
	s_waitcnt lgkmcnt(10)
	v_mfma_f32_16x16x4_f32 v[18:21], v86, v54, v[18:21]
	v_mfma_f32_16x16x4_f32 v[18:21], v87, v55, v[18:21]
	v_mfma_f32_16x16x4_f32 v[18:21], v88, v56, v[18:21]
	v_mfma_f32_16x16x4_f32 v[18:21], v89, v57, v[18:21]
	s_waitcnt lgkmcnt(8)
	v_mfma_f32_16x16x4_f32 v[18:21], v90, v58, v[18:21]
	v_mfma_f32_16x16x4_f32 v[18:21], v91, v59, v[18:21]
	v_mfma_f32_16x16x4_f32 v[18:21], v92, v60, v[18:21]
	v_mfma_f32_16x16x4_f32 v[18:21], v93, v61, v[18:21]
	s_waitcnt lgkmcnt(6)
	v_mfma_f32_16x16x4_f32 v[18:21], v94, v62, v[18:21]
	v_mfma_f32_16x16x4_f32 v[18:21], v95, v63, v[18:21]
	v_mfma_f32_16x16x4_f32 v[18:21], v96, v64, v[18:21]
	v_mfma_f32_16x16x4_f32 v[18:21], v97, v65, v[18:21]
	s_waitcnt lgkmcnt(4)
	v_mfma_f32_16x16x4_f32 v[18:21], v98, v66, v[18:21]
	v_mfma_f32_16x16x4_f32 v[18:21], v99, v67, v[18:21]
	v_mfma_f32_16x16x4_f32 v[18:21], v100, v68, v[18:21]
	v_mfma_f32_16x16x4_f32 v[18:21], v101, v69, v[18:21]
	s_waitcnt lgkmcnt(2)
	v_mfma_f32_16x16x4_f32 v[18:21], v102, v70, v[18:21]
	v_mfma_f32_16x16x4_f32 v[18:21], v103, v71, v[18:21]
	v_mfma_f32_16x16x4_f32 v[18:21], v104, v72, v[18:21]
	v_mfma_f32_16x16x4_f32 v[18:21], v105, v73, v[18:21]
	s_waitcnt lgkmcnt(0)
	v_mfma_f32_16x16x4_f32 v[18:21], v106, v74, v[18:21]
	v_mfma_f32_16x16x4_f32 v[18:21], v107, v75, v[18:21]
	v_mfma_f32_16x16x4_f32 v[18:21], v108, v76, v[18:21]
	v_mfma_f32_16x16x4_f32 v[18:21], v109, v77, v[18:21]
	global_load_dwordx4 v[22:25], v[130:131], off
	s_and_b64 vcc, exec, s[52:53]
	s_waitcnt vmcnt(0)
	s_nop 5
	v_pk_add_f32 v[18:19], v[18:19], v[22:23]
	ds_write2_b32 v155, v18, v19 offset1:1
	v_pk_add_f32 v[18:19], v[20:21], v[24:25]
	ds_write2_b32 v155, v18, v19 offset0:2 offset1:3
	s_waitcnt lgkmcnt(0)
	s_barrier
	s_cbranch_vccz .LBB0_2134
	ds_read2_b32 v[22:23], v154 offset0:8 offset1:9
	ds_read2_b32 v[26:27], v154 offset0:10 offset1:11
	ds_read2_b32 v[28:29], v154 offset0:12 offset1:13
	ds_read2_b32 v[30:31], v154 offset0:14 offset1:15
	ds_read2_b32 v[32:33], v154 offset0:16 offset1:17
	ds_read2_b32 v[34:35], v154 offset0:18 offset1:19
	ds_read2_b32 v[36:37], v154 offset0:20 offset1:21
	ds_read2_b32 v[38:39], v154 offset0:22 offset1:23
	ds_read2_b32 v[40:41], v154 offset0:2 offset1:3
	ds_read2_b32 v[42:43], v154 offset0:4 offset1:5
	ds_read2_b32 v[44:45], v154 offset0:6 offset1:7
	ds_read2_b32 v[46:47], v154 offset1:1
	ds_read2_b32 v[48:49], v154 offset0:24 offset1:25
	ds_read2_b32 v[50:51], v154 offset0:26 offset1:27
	ds_read2_b32 v[52:53], v154 offset0:28 offset1:29
	ds_read2_b32 v[20:21], v154 offset0:30 offset1:31
	s_waitcnt lgkmcnt(4)
	v_cmp_gt_f32_e32 vcc, v47, v46
	v_mov_b32_e32 v25, 0
	s_nop 0
	v_cndmask_b32_e32 v19, v46, v47, vcc
	v_cndmask_b32_e64 v18, 0, 1, vcc
	v_cmp_gt_f32_e32 vcc, v40, v19
	s_nop 1
	v_cndmask_b32_e32 v19, v19, v40, vcc
	v_cndmask_b32_e64 v18, v18, 2, vcc
	v_cmp_gt_f32_e32 vcc, v41, v19
	s_nop 1
	v_cndmask_b32_e32 v19, v19, v41, vcc
	v_cndmask_b32_e64 v18, v18, 3, vcc
	v_cmp_gt_f32_e32 vcc, v42, v19
	s_nop 1
	v_cndmask_b32_e32 v19, v19, v42, vcc
	v_cndmask_b32_e64 v18, v18, 4, vcc
	v_cmp_gt_f32_e32 vcc, v43, v19
	s_nop 1
	v_cndmask_b32_e32 v19, v19, v43, vcc
	v_cndmask_b32_e64 v18, v18, 5, vcc
	v_cmp_gt_f32_e32 vcc, v44, v19
	s_nop 1
	v_cndmask_b32_e32 v19, v19, v44, vcc
	v_cndmask_b32_e64 v18, v18, 6, vcc
	v_cmp_gt_f32_e32 vcc, v45, v19
	s_nop 1
	v_cndmask_b32_e32 v19, v19, v45, vcc
	v_cndmask_b32_e64 v18, v18, 7, vcc
	v_cmp_gt_f32_e32 vcc, v22, v19
	s_nop 1
	v_cndmask_b32_e32 v19, v19, v22, vcc
	v_cndmask_b32_e64 v18, v18, 8, vcc
	v_cmp_gt_f32_e32 vcc, v23, v19
	s_nop 1
	v_cndmask_b32_e32 v19, v19, v23, vcc
	v_cndmask_b32_e64 v18, v18, 9, vcc
	v_cmp_gt_f32_e32 vcc, v26, v19
	s_nop 1
	v_cndmask_b32_e32 v19, v19, v26, vcc
	v_cndmask_b32_e64 v18, v18, 10, vcc
	v_cmp_gt_f32_e32 vcc, v27, v19
	s_nop 1
	v_cndmask_b32_e32 v19, v19, v27, vcc
	v_cndmask_b32_e64 v18, v18, 11, vcc
	v_cmp_gt_f32_e32 vcc, v28, v19
	s_nop 1
	v_cndmask_b32_e32 v19, v19, v28, vcc
	v_cndmask_b32_e64 v18, v18, 12, vcc
	v_cmp_gt_f32_e32 vcc, v29, v19
	s_nop 1
	v_cndmask_b32_e32 v19, v19, v29, vcc
	v_cndmask_b32_e64 v18, v18, 13, vcc
	v_cmp_gt_f32_e32 vcc, v30, v19
	s_nop 1
	v_cndmask_b32_e32 v19, v19, v30, vcc
	v_cndmask_b32_e64 v18, v18, 14, vcc
	v_cmp_gt_f32_e32 vcc, v31, v19
	s_nop 1
	v_cndmask_b32_e32 v19, v19, v31, vcc
	v_cndmask_b32_e64 v18, v18, 15, vcc
	v_cmp_gt_f32_e32 vcc, v32, v19
	s_nop 1
	v_cndmask_b32_e32 v19, v19, v32, vcc
	v_cndmask_b32_e64 v18, v18, 16, vcc
	v_cmp_gt_f32_e32 vcc, v33, v19
	s_nop 1
	v_cndmask_b32_e32 v19, v19, v33, vcc
	v_cndmask_b32_e64 v18, v18, 17, vcc
	v_cmp_gt_f32_e32 vcc, v34, v19
	s_nop 1
	v_cndmask_b32_e32 v19, v19, v34, vcc
	v_cndmask_b32_e64 v18, v18, 18, vcc
	v_cmp_gt_f32_e32 vcc, v35, v19
	s_nop 1
	v_cndmask_b32_e32 v19, v19, v35, vcc
	v_cndmask_b32_e64 v18, v18, 19, vcc
	v_cmp_gt_f32_e32 vcc, v36, v19
	s_nop 1
	v_cndmask_b32_e32 v19, v19, v36, vcc
	v_cndmask_b32_e64 v18, v18, 20, vcc
	v_cmp_gt_f32_e32 vcc, v37, v19
	s_nop 1
	v_cndmask_b32_e32 v19, v19, v37, vcc
	v_cndmask_b32_e64 v18, v18, 21, vcc
	v_cmp_gt_f32_e32 vcc, v38, v19
	s_nop 1
	v_cndmask_b32_e32 v19, v19, v38, vcc
	v_cndmask_b32_e64 v18, v18, 22, vcc
	v_cmp_gt_f32_e32 vcc, v39, v19
	s_nop 1
	v_cndmask_b32_e32 v19, v19, v39, vcc
	v_cndmask_b32_e64 v18, v18, 23, vcc
	s_waitcnt lgkmcnt(3)
; __device__ __forceinline__ void phase_row1(const Frame& F, int l) {
;     ...
;             float tv[4]; int ti[4];
; #pragma unroll
;             for (int r = 0; r < 4; ++r) { float bv = v[0]; int bi = 0;
; #pragma unroll
;                 for (int e = 1; e < 32; ++e) { const bool tk = v[e] > bv; bv = tk ? v[e] : bv; bi = tk ? e : bi; }
;                 tv[r] = bv; ti[r] = bi;
; #pragma unroll
;                 for (int e = 0; e < 32; ++e) v[e] = (e == bi) ? -INFINITY : v[e]; }
	v_cmp_gt_f32_e32 vcc, v48, v19
	s_nop 1
	v_cndmask_b32_e32 v19, v19, v48, vcc
	v_cndmask_b32_e64 v18, v18, 24, vcc
	v_cmp_gt_f32_e32 vcc, v49, v19
	s_nop 1
	v_cndmask_b32_e32 v19, v19, v49, vcc
	v_cndmask_b32_e64 v18, v18, 25, vcc
	s_waitcnt lgkmcnt(2)
	v_cmp_gt_f32_e32 vcc, v50, v19
	s_nop 1
	v_cndmask_b32_e32 v19, v19, v50, vcc
	v_cndmask_b32_e64 v18, v18, 26, vcc
	v_cmp_gt_f32_e32 vcc, v51, v19
	s_nop 1
	v_cndmask_b32_e32 v19, v19, v51, vcc
	v_cndmask_b32_e64 v18, v18, 27, vcc
	s_waitcnt lgkmcnt(1)
	v_cmp_gt_f32_e32 vcc, v52, v19
	s_nop 1
	v_cndmask_b32_e32 v19, v19, v52, vcc
	v_cndmask_b32_e64 v18, v18, 28, vcc
	v_cmp_gt_f32_e32 vcc, v53, v19
	s_nop 1
	v_cndmask_b32_e32 v19, v19, v53, vcc
	v_cndmask_b32_e64 v18, v18, 29, vcc
	s_waitcnt lgkmcnt(0)
	v_cmp_gt_f32_e32 vcc, v20, v19
	s_nop 1
	v_cndmask_b32_e32 v19, v19, v20, vcc
	v_cndmask_b32_e64 v18, v18, 30, vcc
	v_cmp_gt_f32_e32 vcc, v21, v19
	s_nop 1
	v_cndmask_b32_e64 v18, v18, 31, vcc
	v_cmp_ne_u32_e64 s[44:45], 0, v18
	s_nop 1
	v_cndmask_b32_e64 v24, v237, v46, s[44:45]
	v_cmp_ne_u32_e64 s[44:45], 1, v18
	s_nop 1
	v_cndmask_b32_e64 v46, v237, v47, s[44:45]
	v_cmp_ne_u32_e64 s[44:45], 2, v18
	s_nop 1
	v_cndmask_b32_e64 v40, v237, v40, s[44:45]
	v_cmp_ne_u32_e64 s[44:45], 3, v18
	s_nop 1
	v_cndmask_b32_e64 v41, v237, v41, s[44:45]
	v_cmp_ne_u32_e64 s[44:45], 4, v18
	s_nop 1
	v_cndmask_b32_e64 v42, v237, v42, s[44:45]
	v_cmp_ne_u32_e64 s[44:45], 5, v18
	s_nop 1
	v_cndmask_b32_e64 v43, v237, v43, s[44:45]
	v_cmp_ne_u32_e64 s[44:45], 6, v18
	s_nop 1
	v_cndmask_b32_e64 v44, v237, v44, s[44:45]
	v_cmp_ne_u32_e64 s[44:45], 7, v18
	s_nop 1
	v_cndmask_b32_e64 v45, v237, v45, s[44:45]
	v_cmp_ne_u32_e64 s[44:45], 8, v18
	s_nop 1
	v_cndmask_b32_e64 v22, v237, v22, s[44:45]
	v_cmp_ne_u32_e64 s[44:45], 9, v18
	s_nop 1
	v_cndmask_b32_e64 v47, v237, v23, s[44:45]
	v_cmp_ne_u32_e64 s[44:45], 10, v18
	s_nop 1
	v_cndmask_b32_e64 v26, v237, v26, s[44:45]
	v_cmp_ne_u32_e64 s[44:45], 11, v18
	s_nop 1
	v_cndmask_b32_e64 v54, v237, v27, s[44:45]
	v_cmp_ne_u32_e64 s[44:45], 12, v18
	s_nop 1
	v_cndmask_b32_e64 v28, v237, v28, s[44:45]
	v_cmp_ne_u32_e64 s[44:45], 13, v18
	s_nop 1
	v_cndmask_b32_e64 v29, v237, v29, s[44:45]
	v_cmp_ne_u32_e64 s[44:45], 14, v18
	s_nop 1
	v_cndmask_b32_e64 v30, v237, v30, s[44:45]
	v_cmp_ne_u32_e64 s[44:45], 15, v18
	s_nop 1
	v_cndmask_b32_e64 v31, v237, v31, s[44:45]
	v_cmp_ne_u32_e64 s[44:45], 16, v18
	s_nop 1
	v_cndmask_b32_e64 v32, v237, v32, s[44:45]
	v_cmp_ne_u32_e64 s[44:45], 17, v18
	s_nop 1
	v_cndmask_b32_e64 v33, v237, v33, s[44:45]
	v_cmp_ne_u32_e64 s[44:45], 18, v18
	s_nop 1
	v_cndmask_b32_e64 v34, v237, v34, s[44:45]
	v_cmp_ne_u32_e64 s[44:45], 19, v18
	s_nop 1
	v_cndmask_b32_e64 v35, v237, v35, s[44:45]
	v_cmp_ne_u32_e64 s[44:45], 20, v18
	s_nop 1
	v_cndmask_b32_e64 v36, v237, v36, s[44:45]
	v_cmp_ne_u32_e64 s[44:45], 21, v18
	s_nop 1
	v_cndmask_b32_e64 v37, v237, v37, s[44:45]
	v_cmp_ne_u32_e64 s[44:45], 22, v18
	s_nop 1
	v_cndmask_b32_e64 v38, v237, v38, s[44:45]
	v_cmp_ne_u32_e64 s[44:45], 23, v18
	s_nop 1
	v_cndmask_b32_e64 v39, v237, v39, s[44:45]
	v_cmp_ne_u32_e64 s[44:45], 24, v18
	s_nop 1
	v_cndmask_b32_e64 v48, v237, v48, s[44:45]
	v_cmp_ne_u32_e64 s[44:45], 25, v18
	s_nop 1
	v_cndmask_b32_e64 v49, v237, v49, s[44:45]
	v_cmp_ne_u32_e64 s[44:45], 26, v18
	s_nop 1
	v_cndmask_b32_e64 v50, v237, v50, s[44:45]
	v_cmp_ne_u32_e64 s[44:45], 27, v18
	s_nop 1
	v_cndmask_b32_e64 v51, v237, v51, s[44:45]
	v_cmp_ne_u32_e64 s[44:45], 28, v18
	s_nop 1
	v_cndmask_b32_e64 v52, v237, v52, s[44:45]
	v_cmp_ne_u32_e64 s[44:45], 29, v18
	s_nop 1
	v_cndmask_b32_e64 v53, v237, v53, s[44:45]
	v_cmp_ne_u32_e64 s[44:45], 30, v18
	s_nop 1
	v_cndmask_b32_e64 v55, v237, v20, s[44:45]
	v_cmp_ne_u32_e64 s[44:45], 31, v18
	s_nop 1
	v_cndmask_b32_e64 v23, v237, v21, s[44:45]
	v_cmp_gt_f32_e64 s[44:45], v46, v24
	s_nop 1
	v_cndmask_b32_e64 v27, v24, v46, s[44:45]
	v_cndmask_b32_e64 v20, 0, 1, s[44:45]
	v_cmp_gt_f32_e64 s[44:45], v40, v27
	s_nop 1
	v_cndmask_b32_e64 v27, v27, v40, s[44:45]
	v_cndmask_b32_e64 v20, v20, 2, s[44:45]
	v_cmp_gt_f32_e64 s[44:45], v41, v27
	s_nop 1
	v_cndmask_b32_e64 v27, v27, v41, s[44:45]
	v_cndmask_b32_e64 v20, v20, 3, s[44:45]
	v_cmp_gt_f32_e64 s[44:45], v42, v27
	s_nop 1
	v_cndmask_b32_e64 v27, v27, v42, s[44:45]
	v_cndmask_b32_e64 v20, v20, 4, s[44:45]
	v_cmp_gt_f32_e64 s[44:45], v43, v27
	s_nop 1
	v_cndmask_b32_e64 v27, v27, v43, s[44:45]
	v_cndmask_b32_e64 v20, v20, 5, s[44:45]
	v_cmp_gt_f32_e64 s[44:45], v44, v27
	s_nop 1
	v_cndmask_b32_e64 v27, v27, v44, s[44:45]
	v_cndmask_b32_e64 v20, v20, 6, s[44:45]
	v_cmp_gt_f32_e64 s[44:45], v45, v27
	s_nop 1
	v_cndmask_b32_e64 v27, v27, v45, s[44:45]
	v_cndmask_b32_e64 v20, v20, 7, s[44:45]
	v_cmp_gt_f32_e64 s[44:45], v22, v27
	s_nop 1
	v_cndmask_b32_e64 v27, v27, v22, s[44:45]
	v_cndmask_b32_e64 v20, v20, 8, s[44:45]
	v_cmp_gt_f32_e64 s[44:45], v47, v27
	s_nop 1
	v_cndmask_b32_e64 v27, v27, v47, s[44:45]
	v_cndmask_b32_e64 v20, v20, 9, s[44:45]
	v_cmp_gt_f32_e64 s[44:45], v26, v27
	s_nop 1
	v_cndmask_b32_e64 v27, v27, v26, s[44:45]
	v_cndmask_b32_e64 v20, v20, 10, s[44:45]
	v_cmp_gt_f32_e64 s[44:45], v54, v27
	s_nop 1
	v_cndmask_b32_e64 v27, v27, v54, s[44:45]
	v_cndmask_b32_e64 v20, v20, 11, s[44:45]
	v_cmp_gt_f32_e64 s[44:45], v28, v27
	s_nop 1
	v_cndmask_b32_e64 v27, v27, v28, s[44:45]
	v_cndmask_b32_e64 v20, v20, 12, s[44:45]
	v_cmp_gt_f32_e64 s[44:45], v29, v27
	s_nop 1
	v_cndmask_b32_e64 v27, v27, v29, s[44:45]
	v_cndmask_b32_e64 v20, v20, 13, s[44:45]
	v_cmp_gt_f32_e64 s[44:45], v30, v27
	s_nop 1
	v_cndmask_b32_e64 v27, v27, v30, s[44:45]
	v_cndmask_b32_e64 v20, v20, 14, s[44:45]
	v_cmp_gt_f32_e64 s[44:45], v31, v27
; __device__ __forceinline__ void phase_row1(const Frame& F, int l) {
;     ...
;             float tv[4]; int ti[4];
; #pragma unroll
;             for (int r = 0; r < 4; ++r) { float bv = v[0]; int bi = 0;
; #pragma unroll
;                 for (int e = 1; e < 32; ++e) { const bool tk = v[e] > bv; bv = tk ? v[e] : bv; bi = tk ? e : bi; }
;                 tv[r] = bv; ti[r] = bi;
; #pragma unroll
;                 for (int e = 0; e < 32; ++e) v[e] = (e == bi) ? -INFINITY : v[e]; }
	s_nop 1
	v_cndmask_b32_e64 v27, v27, v31, s[44:45]
	v_cndmask_b32_e64 v20, v20, 15, s[44:45]
	v_cmp_gt_f32_e64 s[44:45], v32, v27
	s_nop 1
	v_cndmask_b32_e64 v27, v27, v32, s[44:45]
	v_cndmask_b32_e64 v20, v20, 16, s[44:45]
	v_cmp_gt_f32_e64 s[44:45], v33, v27
	s_nop 1
	v_cndmask_b32_e64 v27, v27, v33, s[44:45]
	v_cndmask_b32_e64 v20, v20, 17, s[44:45]
	v_cmp_gt_f32_e64 s[44:45], v34, v27
	s_nop 1
	v_cndmask_b32_e64 v27, v27, v34, s[44:45]
	v_cndmask_b32_e64 v20, v20, 18, s[44:45]
	v_cmp_gt_f32_e64 s[44:45], v35, v27
	s_nop 1
	v_cndmask_b32_e64 v27, v27, v35, s[44:45]
	v_cndmask_b32_e64 v20, v20, 19, s[44:45]
	v_cmp_gt_f32_e64 s[44:45], v36, v27
	s_nop 1
	v_cndmask_b32_e64 v27, v27, v36, s[44:45]
	v_cndmask_b32_e64 v20, v20, 20, s[44:45]
	v_cmp_gt_f32_e64 s[44:45], v37, v27
	s_nop 1
	v_cndmask_b32_e64 v27, v27, v37, s[44:45]
	v_cndmask_b32_e64 v20, v20, 21, s[44:45]
	v_cmp_gt_f32_e64 s[44:45], v38, v27
	s_nop 1
	v_cndmask_b32_e64 v27, v27, v38, s[44:45]
	v_cndmask_b32_e64 v20, v20, 22, s[44:45]
	v_cmp_gt_f32_e64 s[44:45], v39, v27
	s_nop 1
	v_cndmask_b32_e64 v27, v27, v39, s[44:45]
	v_cndmask_b32_e64 v20, v20, 23, s[44:45]
	v_cmp_gt_f32_e64 s[44:45], v48, v27
	s_nop 1
	v_cndmask_b32_e64 v27, v27, v48, s[44:45]
	v_cndmask_b32_e64 v20, v20, 24, s[44:45]
	v_cmp_gt_f32_e64 s[44:45], v49, v27
	s_nop 1
	v_cndmask_b32_e64 v27, v27, v49, s[44:45]
	v_cndmask_b32_e64 v20, v20, 25, s[44:45]
	v_cmp_gt_f32_e64 s[44:45], v50, v27
	s_nop 1
	v_cndmask_b32_e64 v27, v27, v50, s[44:45]
	v_cndmask_b32_e64 v20, v20, 26, s[44:45]
	v_cmp_gt_f32_e64 s[44:45], v51, v27
	s_nop 1
	v_cndmask_b32_e64 v27, v27, v51, s[44:45]
	v_cndmask_b32_e64 v20, v20, 27, s[44:45]
	v_cmp_gt_f32_e64 s[44:45], v52, v27
	s_nop 1
	v_cndmask_b32_e64 v27, v27, v52, s[44:45]
	v_cndmask_b32_e64 v20, v20, 28, s[44:45]
	v_cmp_gt_f32_e64 s[44:45], v53, v27
	s_nop 1
	v_cndmask_b32_e64 v27, v27, v53, s[44:45]
	v_cndmask_b32_e64 v20, v20, 29, s[44:45]
	v_cmp_gt_f32_e64 s[44:45], v55, v27
	s_nop 1
	v_cndmask_b32_e64 v27, v27, v55, s[44:45]
	v_cndmask_b32_e64 v20, v20, 30, s[44:45]
	v_cmp_gt_f32_e64 s[44:45], v23, v27
	s_nop 1
	v_cndmask_b32_e64 v20, v20, 31, s[44:45]
	v_cmp_ne_u32_e64 s[46:47], 0, v20
	s_nop 1
	v_cndmask_b32_e64 v24, v237, v24, s[46:47]
	v_cmp_ne_u32_e64 s[46:47], 1, v20
	s_nop 1
	v_cndmask_b32_e64 v46, v237, v46, s[46:47]
	v_cmp_ne_u32_e64 s[46:47], 2, v20
	s_nop 1
	v_cndmask_b32_e64 v40, v237, v40, s[46:47]
	v_cmp_ne_u32_e64 s[46:47], 3, v20
	s_nop 1
	v_cndmask_b32_e64 v41, v237, v41, s[46:47]
	v_cmp_ne_u32_e64 s[46:47], 4, v20
	s_nop 1
	v_cndmask_b32_e64 v42, v237, v42, s[46:47]
	v_cmp_ne_u32_e64 s[46:47], 5, v20
	s_nop 1
	v_cndmask_b32_e64 v43, v237, v43, s[46:47]
	v_cmp_ne_u32_e64 s[46:47], 6, v20
	s_nop 1
	v_cndmask_b32_e64 v44, v237, v44, s[46:47]
	v_cmp_ne_u32_e64 s[46:47], 7, v20
	s_nop 1
	v_cndmask_b32_e64 v45, v237, v45, s[46:47]
	v_cmp_ne_u32_e64 s[46:47], 8, v20
	s_nop 1
	v_cndmask_b32_e64 v56, v237, v22, s[46:47]
	v_cmp_ne_u32_e64 s[46:47], 9, v20
	s_nop 1
	v_cndmask_b32_e64 v47, v237, v47, s[46:47]
	v_cmp_ne_u32_e64 s[46:47], 10, v20
	s_nop 1
	v_cndmask_b32_e64 v26, v237, v26, s[46:47]
	v_cmp_ne_u32_e64 s[46:47], 11, v20
	s_nop 1
	v_cndmask_b32_e64 v54, v237, v54, s[46:47]
	v_cmp_ne_u32_e64 s[46:47], 12, v20
	s_nop 1
	v_cndmask_b32_e64 v28, v237, v28, s[46:47]
	v_cmp_ne_u32_e64 s[46:47], 13, v20
	s_nop 1
	v_cndmask_b32_e64 v57, v237, v29, s[46:47]
	v_cmp_ne_u32_e64 s[46:47], 14, v20
	s_nop 1
	v_cndmask_b32_e64 v30, v237, v30, s[46:47]
	v_cmp_ne_u32_e64 s[46:47], 15, v20
	s_nop 1
	v_cndmask_b32_e64 v58, v237, v31, s[46:47]
	v_cmp_ne_u32_e64 s[46:47], 16, v20
	s_nop 1
	v_cndmask_b32_e64 v32, v237, v32, s[46:47]
	v_cmp_ne_u32_e64 s[46:47], 17, v20
	s_nop 1
	v_cndmask_b32_e64 v33, v237, v33, s[46:47]
	v_cmp_ne_u32_e64 s[46:47], 18, v20
	s_nop 1
	v_cndmask_b32_e64 v34, v237, v34, s[46:47]
	v_cmp_ne_u32_e64 s[46:47], 19, v20
	s_nop 1
	v_cndmask_b32_e64 v35, v237, v35, s[46:47]
	v_cmp_ne_u32_e64 s[46:47], 20, v20
	s_nop 1
	v_cndmask_b32_e64 v36, v237, v36, s[46:47]
	v_cmp_ne_u32_e64 s[46:47], 21, v20
	s_nop 1
	v_cndmask_b32_e64 v37, v237, v37, s[46:47]
	v_cmp_ne_u32_e64 s[46:47], 22, v20
	s_nop 1
	v_cndmask_b32_e64 v38, v237, v38, s[46:47]
	v_cmp_ne_u32_e64 s[46:47], 23, v20
	s_nop 1
	v_cndmask_b32_e64 v39, v237, v39, s[46:47]
	v_cmp_ne_u32_e64 s[46:47], 24, v20
	s_nop 1
	v_cndmask_b32_e64 v48, v237, v48, s[46:47]
	v_cmp_ne_u32_e64 s[46:47], 25, v20
	s_nop 1
	v_cndmask_b32_e64 v49, v237, v49, s[46:47]
	v_cmp_ne_u32_e64 s[46:47], 26, v20
	s_nop 1
	v_cndmask_b32_e64 v50, v237, v50, s[46:47]
	v_cmp_ne_u32_e64 s[46:47], 27, v20
	s_nop 1
	v_cndmask_b32_e64 v51, v237, v51, s[46:47]
	v_cmp_ne_u32_e64 s[46:47], 28, v20
	s_nop 1
	v_cndmask_b32_e64 v52, v237, v52, s[46:47]
	v_cmp_ne_u32_e64 s[46:47], 29, v20
	s_nop 1
	v_cndmask_b32_e64 v53, v237, v53, s[46:47]
	v_cmp_ne_u32_e64 s[46:47], 30, v20
	s_nop 1
	v_cndmask_b32_e64 v55, v237, v55, s[46:47]
	v_cmp_ne_u32_e64 s[46:47], 31, v20
	s_nop 1
	v_cndmask_b32_e64 v29, v237, v23, s[46:47]
	v_cmp_gt_f32_e64 s[46:47], v46, v24
	s_nop 1
	v_cndmask_b32_e64 v31, v24, v46, s[46:47]
	v_cndmask_b32_e64 v22, 0, 1, s[46:47]
	v_cmp_gt_f32_e64 s[46:47], v40, v31
	s_nop 1
	v_cndmask_b32_e64 v31, v31, v40, s[46:47]
	v_cndmask_b32_e64 v22, v22, 2, s[46:47]
	v_cmp_gt_f32_e64 s[46:47], v41, v31
	s_nop 1
	v_cndmask_b32_e64 v31, v31, v41, s[46:47]
	v_cndmask_b32_e64 v22, v22, 3, s[46:47]
	v_cmp_gt_f32_e64 s[46:47], v42, v31
	s_nop 1
	v_cndmask_b32_e64 v31, v31, v42, s[46:47]
	v_cndmask_b32_e64 v22, v22, 4, s[46:47]
	v_cmp_gt_f32_e64 s[46:47], v43, v31
	s_nop 1
	v_cndmask_b32_e64 v31, v31, v43, s[46:47]
	v_cndmask_b32_e64 v22, v22, 5, s[46:47]
; __device__ __forceinline__ void phase_row1(const Frame& F, int l) {
;     ...
;             float tv[4]; int ti[4];
; #pragma unroll
;             for (int r = 0; r < 4; ++r) { float bv = v[0]; int bi = 0;
; #pragma unroll
;                 for (int e = 1; e < 32; ++e) { const bool tk = v[e] > bv; bv = tk ? v[e] : bv; bi = tk ? e : bi; }
;                 tv[r] = bv; ti[r] = bi;
; #pragma unroll
;                 for (int e = 0; e < 32; ++e) v[e] = (e == bi) ? -INFINITY : v[e]; }
	v_cmp_gt_f32_e64 s[46:47], v44, v31
	s_nop 1
	v_cndmask_b32_e64 v31, v31, v44, s[46:47]
	v_cndmask_b32_e64 v22, v22, 6, s[46:47]
	v_cmp_gt_f32_e64 s[46:47], v45, v31
	s_nop 1
	v_cndmask_b32_e64 v31, v31, v45, s[46:47]
	v_cndmask_b32_e64 v22, v22, 7, s[46:47]
	v_cmp_gt_f32_e64 s[46:47], v56, v31
	s_nop 1
	v_cndmask_b32_e64 v31, v31, v56, s[46:47]
	v_cndmask_b32_e64 v22, v22, 8, s[46:47]
	v_cmp_gt_f32_e64 s[46:47], v47, v31
	s_nop 1
	v_cndmask_b32_e64 v31, v31, v47, s[46:47]
	v_cndmask_b32_e64 v22, v22, 9, s[46:47]
	v_cmp_gt_f32_e64 s[46:47], v26, v31
	s_nop 1
	v_cndmask_b32_e64 v31, v31, v26, s[46:47]
	v_cndmask_b32_e64 v22, v22, 10, s[46:47]
	v_cmp_gt_f32_e64 s[46:47], v54, v31
	s_nop 1
	v_cndmask_b32_e64 v31, v31, v54, s[46:47]
	v_cndmask_b32_e64 v22, v22, 11, s[46:47]
	v_cmp_gt_f32_e64 s[46:47], v28, v31
	s_nop 1
	v_cndmask_b32_e64 v31, v31, v28, s[46:47]
	v_cndmask_b32_e64 v22, v22, 12, s[46:47]
	v_cmp_gt_f32_e64 s[46:47], v57, v31
	s_nop 1
	v_cndmask_b32_e64 v31, v31, v57, s[46:47]
	v_cndmask_b32_e64 v22, v22, 13, s[46:47]
	v_cmp_gt_f32_e64 s[46:47], v30, v31
	s_nop 1
	v_cndmask_b32_e64 v31, v31, v30, s[46:47]
	v_cndmask_b32_e64 v22, v22, 14, s[46:47]
	v_cmp_gt_f32_e64 s[46:47], v58, v31
	s_nop 1
	v_cndmask_b32_e64 v31, v31, v58, s[46:47]
	v_cndmask_b32_e64 v22, v22, 15, s[46:47]
	v_cmp_gt_f32_e64 s[46:47], v32, v31
	s_nop 1
	v_cndmask_b32_e64 v31, v31, v32, s[46:47]
	v_cndmask_b32_e64 v22, v22, 16, s[46:47]
	v_cmp_gt_f32_e64 s[46:47], v33, v31
	s_nop 1
	v_cndmask_b32_e64 v31, v31, v33, s[46:47]
	v_cndmask_b32_e64 v22, v22, 17, s[46:47]
	v_cmp_gt_f32_e64 s[46:47], v34, v31
	s_nop 1
	v_cndmask_b32_e64 v31, v31, v34, s[46:47]
	v_cndmask_b32_e64 v22, v22, 18, s[46:47]
	v_cmp_gt_f32_e64 s[46:47], v35, v31
	s_nop 1
	v_cndmask_b32_e64 v31, v31, v35, s[46:47]
	v_cndmask_b32_e64 v22, v22, 19, s[46:47]
	v_cmp_gt_f32_e64 s[46:47], v36, v31
	s_nop 1
	v_cndmask_b32_e64 v31, v31, v36, s[46:47]
	v_cndmask_b32_e64 v22, v22, 20, s[46:47]
	v_cmp_gt_f32_e64 s[46:47], v37, v31
	s_nop 1
	v_cndmask_b32_e64 v31, v31, v37, s[46:47]
	v_cndmask_b32_e64 v22, v22, 21, s[46:47]
	v_cmp_gt_f32_e64 s[46:47], v38, v31
	s_nop 1
	v_cndmask_b32_e64 v31, v31, v38, s[46:47]
	v_cndmask_b32_e64 v22, v22, 22, s[46:47]
	v_cmp_gt_f32_e64 s[46:47], v39, v31
	s_nop 1
	v_cndmask_b32_e64 v31, v31, v39, s[46:47]
	v_cndmask_b32_e64 v22, v22, 23, s[46:47]
	v_cmp_gt_f32_e64 s[46:47], v48, v31
	s_nop 1
	v_cndmask_b32_e64 v31, v31, v48, s[46:47]
	v_cndmask_b32_e64 v22, v22, 24, s[46:47]
	v_cmp_gt_f32_e64 s[46:47], v49, v31
	s_nop 1
	v_cndmask_b32_e64 v31, v31, v49, s[46:47]
	v_cndmask_b32_e64 v22, v22, 25, s[46:47]
	v_cmp_gt_f32_e64 s[46:47], v50, v31
	s_nop 1
	v_cndmask_b32_e64 v31, v31, v50, s[46:47]
	v_cndmask_b32_e64 v22, v22, 26, s[46:47]
	v_cmp_gt_f32_e64 s[46:47], v51, v31
	s_nop 1
	v_cndmask_b32_e64 v31, v31, v51, s[46:47]
	v_cndmask_b32_e64 v22, v22, 27, s[46:47]
	v_cmp_gt_f32_e64 s[46:47], v52, v31
	s_nop 1
	v_cndmask_b32_e64 v31, v31, v52, s[46:47]
	v_cndmask_b32_e64 v22, v22, 28, s[46:47]
	v_cmp_gt_f32_e64 s[46:47], v53, v31
	s_nop 1
	v_cndmask_b32_e64 v31, v31, v53, s[46:47]
	v_cndmask_b32_e64 v22, v22, 29, s[46:47]
	v_cmp_gt_f32_e64 s[46:47], v55, v31
	s_nop 1
	v_cndmask_b32_e64 v31, v31, v55, s[46:47]
	v_cndmask_b32_e64 v22, v22, 30, s[46:47]
	v_cmp_gt_f32_e64 s[46:47], v29, v31
	s_nop 1
	v_cndmask_b32_e64 v22, v22, 31, s[46:47]
	v_cmp_ne_u32_e64 s[48:49], 0, v22
	s_nop 1
	v_cndmask_b32_e64 v24, v237, v24, s[48:49]
	v_cmp_ne_u32_e64 s[48:49], 1, v22
	s_nop 1
	v_cndmask_b32_e64 v46, v237, v46, s[48:49]
	v_cmp_ne_u32_e64 s[48:49], 2, v22
	s_nop 1
	v_cndmask_b32_e64 v40, v237, v40, s[48:49]
	v_cmp_ne_u32_e64 s[48:49], 3, v22
	s_nop 1
	v_cndmask_b32_e64 v41, v237, v41, s[48:49]
	v_cmp_ne_u32_e64 s[48:49], 4, v22
	s_nop 1
	v_cndmask_b32_e64 v42, v237, v42, s[48:49]
	v_cmp_ne_u32_e64 s[48:49], 5, v22
	s_nop 1
	v_cndmask_b32_e64 v43, v237, v43, s[48:49]
	v_cmp_ne_u32_e64 s[48:49], 6, v22
	s_nop 1
	v_cndmask_b32_e64 v44, v237, v44, s[48:49]
	v_cmp_ne_u32_e64 s[48:49], 7, v22
	s_nop 1
	v_cndmask_b32_e64 v45, v237, v45, s[48:49]
	v_cmp_ne_u32_e64 s[48:49], 8, v22
	s_nop 1
	v_cndmask_b32_e64 v56, v237, v56, s[48:49]
	v_cmp_ne_u32_e64 s[48:49], 9, v22
	s_nop 1
	v_cndmask_b32_e64 v47, v237, v47, s[48:49]
	v_cmp_ne_u32_e64 s[48:49], 10, v22
	s_nop 1
	v_cndmask_b32_e64 v26, v237, v26, s[48:49]
	v_cmp_ne_u32_e64 s[48:49], 11, v22
	s_nop 1
	v_cndmask_b32_e64 v54, v237, v54, s[48:49]
	v_cmp_ne_u32_e64 s[48:49], 12, v22
	s_nop 1
	v_cndmask_b32_e64 v28, v237, v28, s[48:49]
	v_cmp_ne_u32_e64 s[48:49], 13, v22
	s_nop 1
	v_cndmask_b32_e64 v57, v237, v57, s[48:49]
	v_cmp_ne_u32_e64 s[48:49], 14, v22
	s_nop 1
	v_cndmask_b32_e64 v30, v237, v30, s[48:49]
	v_cmp_ne_u32_e64 s[48:49], 15, v22
	s_nop 1
	v_cndmask_b32_e64 v58, v237, v58, s[48:49]
	v_cmp_ne_u32_e64 s[48:49], 16, v22
	s_nop 1
	v_cndmask_b32_e64 v59, v237, v32, s[48:49]
	v_cmp_ne_u32_e64 s[48:49], 17, v22
	s_nop 1
	v_cndmask_b32_e64 v60, v237, v33, s[48:49]
	v_cmp_ne_u32_e64 s[48:49], 18, v22
	s_nop 1
	v_cndmask_b32_e64 v34, v237, v34, s[48:49]
	v_cmp_ne_u32_e64 s[48:49], 19, v22
	s_nop 1
	v_cndmask_b32_e64 v61, v237, v35, s[48:49]
	v_cmp_ne_u32_e64 s[48:49], 20, v22
	s_nop 1
	v_cndmask_b32_e64 v62, v237, v36, s[48:49]
	v_cmp_ne_u32_e64 s[48:49], 21, v22
	s_nop 1
	v_cndmask_b32_e64 v63, v237, v37, s[48:49]
	v_cmp_ne_u32_e64 s[48:49], 22, v22
	s_nop 1
	v_cndmask_b32_e64 v38, v237, v38, s[48:49]
	v_cmp_ne_u32_e64 s[48:49], 23, v22
	s_nop 1
	v_cndmask_b32_e64 v39, v237, v39, s[48:49]
; #define LAS __attribute__((address_space(3)))
; #define LDS_WAIT() asm volatile("s_waitcnt lgkmcnt(0)" ::: "memory")
; __device__ __forceinline__ void phase_row1(const Frame& F, int l) {
;     ...
;             float tv[4]; int ti[4];
; #pragma unroll
;             for (int r = 0; r < 4; ++r) { float bv = v[0]; int bi = 0;
; #pragma unroll
;                 for (int e = 1; e < 32; ++e) { const bool tk = v[e] > bv; bv = tk ? v[e] : bv; bi = tk ? e : bi; }
;                 tv[r] = bv; ti[r] = bi;
; #pragma unroll
;                 for (int e = 0; e < 32; ++e) v[e] = (e == bi) ? -INFINITY : v[e]; }
;             float ev[4], es = 0.f;
; #pragma unroll
;             for (int r = 0; r < 4; ++r) { ev[r] = expf(tv[r] - tv[0]); es += ev[r]; }
;             const float rowscale = ((const float*)(F.ws + WS_HS))[row];
;             int lp[4];
; #pragma unroll
;             for (int r = 0; r < 4; ++r) lp[r] = __hip_atomic_fetch_add((LAS int*)(F.lds + 16384) + ti[r], 1, __ATOMIC_RELAXED, __HIP_MEMORY_SCOPE_WORKGROUP);
;             LDS_WAIT();
;             int base = 0;
;             if (lane < 32) { const int c = lc[lane]; unsigned* cnt = (unsigned*)(F.ws + WS_CTL) + CW_CNT + l * NE; base = c > 0 ? (int)atomicAdd(cnt + lane, (unsigned)c) : 0; }
	v_cmp_ne_u32_e64 s[48:49], 24, v22
	s_nop 1
	v_cndmask_b32_e64 v48, v237, v48, s[48:49]
	v_cmp_ne_u32_e64 s[48:49], 25, v22
	s_nop 1
	v_cndmask_b32_e64 v49, v237, v49, s[48:49]
	v_cmp_ne_u32_e64 s[48:49], 26, v22
	s_nop 1
	v_cndmask_b32_e64 v50, v237, v50, s[48:49]
	v_cmp_ne_u32_e64 s[48:49], 27, v22
	s_nop 1
	v_cndmask_b32_e64 v51, v237, v51, s[48:49]
	v_cmp_ne_u32_e64 s[48:49], 28, v22
	s_nop 1
	v_cndmask_b32_e64 v52, v237, v52, s[48:49]
	v_cmp_ne_u32_e64 s[48:49], 29, v22
	s_nop 1
	v_cndmask_b32_e64 v53, v237, v53, s[48:49]
	v_cmp_ne_u32_e64 s[48:49], 30, v22
	s_nop 1
	v_cndmask_b32_e64 v55, v237, v55, s[48:49]
	v_cmp_ne_u32_e64 s[48:49], 31, v22
	s_nop 1
	v_cndmask_b32_e64 v35, v237, v29, s[48:49]
	v_cmp_gt_f32_e64 s[48:49], v46, v24
	s_nop 1
	v_cndmask_b32_e64 v24, v24, v46, s[48:49]
	v_cndmask_b32_e64 v32, 0, 1, s[48:49]
	v_cmp_gt_f32_e64 s[48:49], v40, v24
	s_nop 1
	v_cndmask_b32_e64 v24, v24, v40, s[48:49]
	v_cndmask_b32_e64 v32, v32, 2, s[48:49]
	v_cmp_gt_f32_e64 s[48:49], v41, v24
	s_nop 1
	v_cndmask_b32_e64 v24, v24, v41, s[48:49]
	v_cndmask_b32_e64 v32, v32, 3, s[48:49]
	v_cmp_gt_f32_e64 s[48:49], v42, v24
	s_nop 1
	v_cndmask_b32_e64 v24, v24, v42, s[48:49]
	v_cndmask_b32_e64 v32, v32, 4, s[48:49]
	v_cmp_gt_f32_e64 s[48:49], v43, v24
	s_nop 1
	v_cndmask_b32_e64 v24, v24, v43, s[48:49]
	v_cndmask_b32_e64 v32, v32, 5, s[48:49]
	v_cmp_gt_f32_e64 s[48:49], v44, v24
	s_nop 1
	v_cndmask_b32_e64 v24, v24, v44, s[48:49]
	v_cndmask_b32_e64 v32, v32, 6, s[48:49]
	v_cmp_gt_f32_e64 s[48:49], v45, v24
	s_nop 1
	v_cndmask_b32_e64 v24, v24, v45, s[48:49]
	v_cndmask_b32_e64 v32, v32, 7, s[48:49]
	v_cmp_gt_f32_e64 s[48:49], v56, v24
	s_nop 1
	v_cndmask_b32_e64 v40, v32, 8, s[48:49]
	v_or_b32_e32 v32, s3, v1
	v_ashrrev_i32_e32 v33, 31, v32
	v_lshl_add_u64 v[36:37], v[32:33], 2, s[54:55]
	global_load_dword v36, v[36:37], off
	v_cndmask_b32_e64 v24, v24, v56, s[48:49]
	v_cmp_gt_f32_e64 s[48:49], v47, v24
	s_nop 1
	v_cndmask_b32_e64 v24, v24, v47, s[48:49]
	v_cndmask_b32_e64 v33, v40, 9, s[48:49]
	v_cmp_gt_f32_e64 s[48:49], v26, v24
	s_nop 1
	v_cndmask_b32_e64 v24, v24, v26, s[48:49]
	v_cndmask_b32_e64 v33, v33, 10, s[48:49]
	v_cmp_gt_f32_e64 s[48:49], v54, v24
	s_nop 1
	v_cndmask_b32_e64 v24, v24, v54, s[48:49]
	v_cndmask_b32_e64 v26, v33, 11, s[48:49]
	v_cmp_gt_f32_e64 s[48:49], v28, v24
	s_nop 1
	v_cndmask_b32_e64 v24, v24, v28, s[48:49]
	v_cndmask_b32_e64 v26, v26, 12, s[48:49]
	v_cmp_gt_f32_e64 s[48:49], v57, v24
	s_nop 1
	v_cndmask_b32_e64 v24, v24, v57, s[48:49]
	v_cndmask_b32_e64 v26, v26, 13, s[48:49]
	v_cmp_gt_f32_e64 s[48:49], v30, v24
	s_nop 1
	v_cndmask_b32_e64 v24, v24, v30, s[48:49]
	v_cndmask_b32_e64 v26, v26, 14, s[48:49]
	v_cmp_gt_f32_e64 s[48:49], v58, v24
	s_nop 1
	v_cndmask_b32_e64 v24, v24, v58, s[48:49]
	v_cndmask_b32_e64 v26, v26, 15, s[48:49]
	v_cmp_gt_f32_e64 s[48:49], v59, v24
	s_nop 1
	v_cndmask_b32_e64 v24, v24, v59, s[48:49]
	v_cndmask_b32_e64 v26, v26, 16, s[48:49]
	v_cmp_gt_f32_e64 s[48:49], v60, v24
	s_nop 1
	v_cndmask_b32_e64 v24, v24, v60, s[48:49]
	v_cndmask_b32_e64 v26, v26, 17, s[48:49]
	v_cmp_gt_f32_e64 s[48:49], v34, v24
	s_nop 1
	v_cndmask_b32_e64 v24, v24, v34, s[48:49]
	v_cndmask_b32_e64 v26, v26, 18, s[48:49]
	v_cmp_gt_f32_e64 s[48:49], v61, v24
	s_nop 1
	v_cndmask_b32_e64 v24, v24, v61, s[48:49]
	v_cndmask_b32_e64 v26, v26, 19, s[48:49]
	v_cmp_gt_f32_e64 s[48:49], v62, v24
	s_nop 1
	v_cndmask_b32_e64 v24, v24, v62, s[48:49]
	v_cndmask_b32_e64 v26, v26, 20, s[48:49]
	v_cmp_gt_f32_e64 s[48:49], v63, v24
	s_nop 1
	v_cndmask_b32_e64 v24, v24, v63, s[48:49]
	v_cndmask_b32_e64 v26, v26, 21, s[48:49]
	v_cmp_gt_f32_e64 s[48:49], v38, v24
	s_nop 1
	v_cndmask_b32_e64 v24, v24, v38, s[48:49]
	v_cndmask_b32_e64 v26, v26, 22, s[48:49]
	v_cmp_gt_f32_e64 s[48:49], v39, v24
	s_nop 1
	v_cndmask_b32_e64 v24, v24, v39, s[48:49]
	v_cndmask_b32_e64 v26, v26, 23, s[48:49]
	v_cmp_gt_f32_e64 s[48:49], v48, v24
	s_nop 1
	v_cndmask_b32_e64 v24, v24, v48, s[48:49]
	v_cndmask_b32_e64 v26, v26, 24, s[48:49]
	v_cmp_gt_f32_e64 s[48:49], v49, v24
	s_nop 1
	v_cndmask_b32_e64 v24, v24, v49, s[48:49]
	v_cndmask_b32_e64 v26, v26, 25, s[48:49]
	v_cmp_gt_f32_e64 s[48:49], v50, v24
	s_nop 1
	v_cndmask_b32_e64 v24, v24, v50, s[48:49]
	v_cndmask_b32_e64 v26, v26, 26, s[48:49]
	v_cmp_gt_f32_e64 s[48:49], v51, v24
	s_nop 1
	v_cndmask_b32_e64 v24, v24, v51, s[48:49]
	v_cndmask_b32_e64 v26, v26, 27, s[48:49]
	v_cmp_gt_f32_e64 s[48:49], v52, v24
	s_nop 1
	v_cndmask_b32_e64 v24, v24, v52, s[48:49]
	v_cndmask_b32_e64 v26, v26, 28, s[48:49]
	v_cmp_gt_f32_e64 s[48:49], v53, v24
	s_nop 1
	v_cndmask_b32_e64 v24, v24, v53, s[48:49]
	v_cndmask_b32_e64 v26, v26, 29, s[48:49]
	v_cmp_gt_f32_e64 s[48:49], v55, v24
	s_nop 1
	v_cndmask_b32_e64 v33, v24, v55, s[48:49]
	v_cndmask_b32_e64 v26, v26, 30, s[48:49]
	v_cmp_gt_f32_e64 s[48:49], v35, v33
	s_nop 1
	v_cndmask_b32_e64 v24, v26, 31, s[48:49]
	v_lshl_add_u32 v26, v18, 2, 0
	ds_add_rtn_u32 v34, v26, v222 offset:16384
	v_lshl_add_u32 v26, v20, 2, 0
	ds_add_rtn_u32 v30, v26, v222 offset:16384
	v_lshl_add_u32 v26, v22, 2, 0
	ds_add_rtn_u32 v28, v26, v222 offset:16384
	v_lshl_add_u32 v26, v24, 2, 0
	ds_add_rtn_u32 v26, v26, v222 offset:16384
	s_waitcnt lgkmcnt(0)
	s_and_saveexec_b64 s[4:5], s[40:41]
	s_cbranch_execz .LBB0_2133
	ds_read_b32 v37, v157 offset:16384
	v_mov_b32_e32 v25, 0
	s_waitcnt lgkmcnt(0)
	v_cmp_lt_i32_e64 s[50:51], 0, v37
	s_and_saveexec_b64 s[6:7], s[50:51]
	s_cbranch_execz .LBB0_2132
	global_atomic_add v25, v[122:123], v37, off sc0
	s_branch .LBB0_2132
